# GEMM K loops, second k-step head: literal stage offsets in the fragment address adds; the two SALU constant moves follow the reads
# baseline (speedup 1.0000x reference)
; #define PG8_STAGE(bufoff, gbase, voff) do { _Pragma("unroll") for (int _i = 0; _i < 2; ++_i) \
;         __builtin_amdgcn_global_load_lds((const unsigned*)((const char*)(gbase) + (voff)[_i]), (PG8_LAS unsigned*)(lds + (bufoff) + ldsw + _i * 8192), 16, 0, 0); } while (0)
; #define PG8_LDA(dst, b, h) do { _Pragma("unroll") for (int m = 0; m < 4; ++m) _Pragma("unroll") for (int k = 0; k < 2; ++k) dst[m][k] = *(const PG8_LAS bf16x8*)(lds + PG8_SA(b, h) + aoff + m * 2048 + k * 1024); } while (0)
; #define PG8_LDB(dst, b, h) do { _Pragma("unroll") for (int n = 0; n < 2; ++n) _Pragma("unroll") for (int k = 0; k < 2; ++k) dst[n][k] = *(const PG8_LAS bf16x8*)(lds + PG8_SB(b, h) + boff + n * 2048 + k * 1024); } while (0)
; #define PG8_MMA(ai, bj, At, Bt) do { __builtin_amdgcn_s_setprio(1); _Pragma("unroll") for (int m = 0; m < 4; ++m) _Pragma("unroll") for (int n = 0; n < 2; ++n) _Pragma("unroll") for (int k = 0; k < 2; ++k) \
;         acc[ai][bj][m][n] = __builtin_amdgcn_mfma_f32_16x16x32_bf16(Bt[n][k], At[m][k], acc[ai][bj][m][n], 0, 0, 0); __builtin_amdgcn_s_setprio(0); } while (0)
; #define PG8_WAIT_V(n) asm volatile("s_waitcnt vmcnt(" #n ")" ::: "memory")
; #define PG8_WAIT_L(n) asm volatile("s_waitcnt lgkmcnt(" #n ")" ::: "memory")
; #define PG8_BAR __builtin_amdgcn_s_barrier()
; #define PG8_SCHED __builtin_amdgcn_sched_barrier(0)
; template <class Epi, class Sched, bool ALIGN_EPI = false, bool SP2 = false>
; __device__ __forceinline__ void gemm_phase(PG8_LAS unsigned char* lds, const Gemm g, const Sched S, const Epi E) {
;     ...
;             const bool last = (t == nt - 2);
;             const char* a1 = cA + (size_t)(t + 1) * kstep;
;             const char* a2 = last ? nA : cA + (size_t)(t + 2) * kstep; const char* b2 = last ? nB : cB + (size_t)(t + 2) * kstep;
;             const char* a3 = a2 + kstep; const char* b3 = b2 + kstep;
;             if (last && has_next) S.a_ready(nxt);
;             if constexpr (SP2) {
;             PG8_LDB(B0, 0, 0); PG8_LDB(B1, 0, 1); PG8_SCHED; PG8_LDA(At, 0, 0); PG8_STAGE(PG8_SA(1, 1), a1 + hstep, voffA);
;             PG8_WAIT_V(8); PG8_WAIT_L(0); PG8_BAR; PG8_MMA(0, 0, At, B0); PG8_MMA(0, 1, At, B1); PG8_BAR; PG8_SCHED;
;             PG8_LDA(At, 0, 1); PG8_STAGE(PG8_SB(0, 0), b2, voffB); PG8_STAGE(PG8_SB(0, 1), b2 + hstep, voffB); PG8_STAGE(PG8_SA(0, 0), a2, voffA);
.LBB0_180:
	v_add_u32_e32 v140, 0x10000, v143
	ds_read_b128 v[154:157], v140
	ds_read_b128 v[158:161], v140 offset:1024
	ds_read_b128 v[162:165], v140 offset:2048
	ds_read_b128 v[166:169], v140 offset:3072
	v_add_u32_e32 v140, 0x14000, v143
	ds_read_b128 v[170:173], v140
	ds_read_b128 v[174:177], v140 offset:1024
	ds_read_b128 v[182:185], v140 offset:2048
	ds_read_b128 v[198:201], v140 offset:3072
	s_add_i32 s20, s18, 2
	s_add_u32 s21, s16, 0x80
	s_addc_u32 s19, s17, 0
	s_add_i32 s25, 0, 0x10000
	s_cmp_eq_u32 s75, s18
	s_cselect_b32 s19, s1, s19
	s_cselect_b32 s18, s0, s21
	s_cselect_b32 s23, s59, s15
	s_cselect_b32 s22, s58, s14
	s_add_i32 s21, 0, 0x14000
	v_lshl_add_u64 v[140:141], s[16:17], 0, v[136:137]
	s_add_i32 m0, s68, 0xc000
	ds_read_b128 v[202:205], v146
	ds_read_b128 v[206:209], v146 offset:1024
	ds_read_b128 v[210:213], v146 offset:2048
	ds_read_b128 v[214:217], v146 offset:3072
	ds_read_b128 v[218:221], v146 offset:4096
	ds_read_b128 v[222:225], v146 offset:5120
	ds_read_b128 v[226:229], v146 offset:6144
	ds_read_b128 v[230:233], v146 offset:7168
	global_load_lds_dwordx4 v[140:141], off
	v_lshl_add_u64 v[140:141], s[16:17], 0, v[138:139]
	s_add_i32 m0, s68, 0xe000
	s_nop 0
	global_load_lds_dwordx4 v[140:141], off
	s_waitcnt vmcnt(8)
	s_waitcnt lgkmcnt(0)
	s_barrier
	s_setprio 1
	s_waitcnt lgkmcnt(0)
	v_mfma_f32_16x16x32_bf16 v[126:129], v[154:157], v[202:205], v[126:129]
	v_mfma_f32_16x16x32_bf16 v[118:121], v[162:165], v[202:205], v[118:121]
	v_mfma_f32_16x16x32_bf16 v[110:113], v[154:157], v[210:213], v[110:113]
	v_mfma_f32_16x16x32_bf16 v[102:105], v[162:165], v[210:213], v[102:105]
	v_mfma_f32_16x16x32_bf16 v[94:97], v[154:157], v[218:221], v[94:97]
	v_mfma_f32_16x16x32_bf16 v[86:89], v[162:165], v[218:221], v[86:89]
	v_mfma_f32_16x16x32_bf16 v[78:81], v[154:157], v[226:229], v[78:81]
	v_mfma_f32_16x16x32_bf16 v[70:73], v[162:165], v[226:229], v[70:73]
	v_mfma_f32_16x16x32_bf16 v[126:129], v[158:161], v[206:209], v[126:129]
	v_mfma_f32_16x16x32_bf16 v[118:121], v[166:169], v[206:209], v[118:121]
	v_mfma_f32_16x16x32_bf16 v[110:113], v[158:161], v[214:217], v[110:113]
	v_mfma_f32_16x16x32_bf16 v[102:105], v[166:169], v[214:217], v[102:105]
	v_mfma_f32_16x16x32_bf16 v[94:97], v[158:161], v[222:225], v[94:97]
	v_mfma_f32_16x16x32_bf16 v[86:89], v[166:169], v[222:225], v[86:89]
	v_mfma_f32_16x16x32_bf16 v[78:81], v[158:161], v[230:233], v[78:81]
	v_mfma_f32_16x16x32_bf16 v[70:73], v[166:169], v[230:233], v[70:73]
	s_setprio 0
	s_setprio 1
	v_mfma_f32_16x16x32_bf16 v[122:125], v[170:173], v[202:205], v[122:125]
	v_mfma_f32_16x16x32_bf16 v[114:117], v[182:185], v[202:205], v[114:117]
	v_mfma_f32_16x16x32_bf16 v[106:109], v[170:173], v[210:213], v[106:109]
	v_mfma_f32_16x16x32_bf16 v[98:101], v[182:185], v[210:213], v[98:101]
	v_mfma_f32_16x16x32_bf16 v[90:93], v[170:173], v[218:221], v[90:93]
	v_mfma_f32_16x16x32_bf16 v[82:85], v[182:185], v[218:221], v[82:85]
	v_mfma_f32_16x16x32_bf16 v[74:77], v[170:173], v[226:229], v[74:77]
	v_mfma_f32_16x16x32_bf16 v[66:69], v[182:185], v[226:229], v[66:69]
	v_mfma_f32_16x16x32_bf16 v[122:125], v[174:177], v[206:209], v[122:125]
	v_mfma_f32_16x16x32_bf16 v[114:117], v[198:201], v[206:209], v[114:117]
	v_mfma_f32_16x16x32_bf16 v[106:109], v[174:177], v[214:217], v[106:109]
	v_mfma_f32_16x16x32_bf16 v[98:101], v[198:201], v[214:217], v[98:101]
	v_mfma_f32_16x16x32_bf16 v[90:93], v[174:177], v[222:225], v[90:93]
	v_mfma_f32_16x16x32_bf16 v[82:85], v[198:201], v[222:225], v[82:85]
	v_mfma_f32_16x16x32_bf16 v[74:77], v[174:177], v[230:233], v[74:77]
	v_mfma_f32_16x16x32_bf16 v[66:69], v[198:201], v[230:233], v[66:69]
	s_setprio 0
	s_barrier
	s_add_i32 s25, s25, s61
	v_lshl_add_u64 v[140:141], s[22:23], 0, v[0:1]
	s_mov_b32 m0, s25
	ds_read_b128 v[202:205], v146 offset:16384
	ds_read_b128 v[206:209], v146 offset:17408
	ds_read_b128 v[210:213], v146 offset:18432
	ds_read_b128 v[214:217], v146 offset:19456
	ds_read_b128 v[218:221], v146 offset:20480
	ds_read_b128 v[222:225], v146 offset:21504
	ds_read_b128 v[226:229], v146 offset:22528
	ds_read_b128 v[230:233], v146 offset:23552
	global_load_lds_dwordx4 v[140:141], off
	s_add_i32 m0, s25, 0x2000
	v_lshl_add_u64 v[234:235], s[22:23], 0, v[130:131]
	s_add_u32 s22, s22, s28
	s_addc_u32 s23, s23, 0
	s_add_i32 s21, s21, s61
	global_load_lds_dwordx4 v[234:235], off
	v_lshl_add_u64 v[236:237], s[22:23], 0, v[0:1]
	s_mov_b32 m0, s21
	v_lshl_add_u64 v[238:239], s[22:23], 0, v[130:131]
	global_load_lds_dwordx4 v[236:237], off
	s_add_i32 m0, s21, 0x2000
	v_lshl_add_u64 v[240:241], s[18:19], 0, v[134:135]
	global_load_lds_dwordx4 v[238:239], off
	s_mov_b32 m0, s68
	v_lshl_add_u64 v[242:243], s[18:19], 0, v[132:133]
	global_load_lds_dwordx4 v[240:241], off
	s_mov_b32 m0, s69
	s_nop 0
	global_load_lds_dwordx4 v[242:243], off
	s_waitcnt vmcnt(8)
	s_waitcnt lgkmcnt(0)
	s_barrier
; #define PG8_STAGE(bufoff, gbase, voff) do { _Pragma("unroll") for (int _i = 0; _i < 2; ++_i) \
;         __builtin_amdgcn_global_load_lds((const unsigned*)((const char*)(gbase) + (voff)[_i]), (PG8_LAS unsigned*)(lds + (bufoff) + ldsw + _i * 8192), 16, 0, 0); } while (0)
; #define PG8_LDA(dst, b, h) do { _Pragma("unroll") for (int m = 0; m < 4; ++m) _Pragma("unroll") for (int k = 0; k < 2; ++k) dst[m][k] = *(const PG8_LAS bf16x8*)(lds + PG8_SA(b, h) + aoff + m * 2048 + k * 1024); } while (0)
; #define PG8_LDB(dst, b, h) do { _Pragma("unroll") for (int n = 0; n < 2; ++n) _Pragma("unroll") for (int k = 0; k < 2; ++k) dst[n][k] = *(const PG8_LAS bf16x8*)(lds + PG8_SB(b, h) + boff + n * 2048 + k * 1024); } while (0)
; #define PG8_MMA(ai, bj, At, Bt) do { __builtin_amdgcn_s_setprio(1); _Pragma("unroll") for (int m = 0; m < 4; ++m) _Pragma("unroll") for (int n = 0; n < 2; ++n) _Pragma("unroll") for (int k = 0; k < 2; ++k) \
;         acc[ai][bj][m][n] = __builtin_amdgcn_mfma_f32_16x16x32_bf16(Bt[n][k], At[m][k], acc[ai][bj][m][n], 0, 0, 0); __builtin_amdgcn_s_setprio(0); } while (0)
; #define PG8_WAIT_V(n) asm volatile("s_waitcnt vmcnt(" #n ")" ::: "memory")
; #define PG8_WAIT_L(n) asm volatile("s_waitcnt lgkmcnt(" #n ")" ::: "memory")
; #define PG8_BAR __builtin_amdgcn_s_barrier()
; #define PG8_SCHED __builtin_amdgcn_sched_barrier(0)
; template <class Epi, class Sched, bool ALIGN_EPI = false, bool SP2 = false>
; __device__ __forceinline__ void gemm_phase(PG8_LAS unsigned char* lds, const Gemm g, const Sched S, const Epi E) {
;     ...
;             PG8_WAIT_V(8); PG8_WAIT_L(0); PG8_BAR; PG8_MMA(1, 0, At, B0); PG8_MMA(1, 1, At, B1); PG8_BAR; PG8_SCHED;
;             PG8_LDB(B0, 1, 0); PG8_LDB(B1, 1, 1); PG8_SCHED; PG8_LDA(At, 1, 0); PG8_STAGE(PG8_SA(0, 1), a2 + hstep, voffA);
;             PG8_WAIT_V(8); PG8_WAIT_L(0); PG8_BAR; PG8_MMA(0, 0, At, B0); PG8_MMA(0, 1, At, B1); PG8_BAR; PG8_SCHED;
	s_setprio 1
	s_waitcnt lgkmcnt(0)
	v_mfma_f32_16x16x32_bf16 v[62:65], v[154:157], v[202:205], v[62:65]
	v_mfma_f32_16x16x32_bf16 v[54:57], v[162:165], v[202:205], v[54:57]
	v_mfma_f32_16x16x32_bf16 v[46:49], v[154:157], v[210:213], v[46:49]
	v_mfma_f32_16x16x32_bf16 v[38:41], v[162:165], v[210:213], v[38:41]
	v_mfma_f32_16x16x32_bf16 v[30:33], v[154:157], v[218:221], v[30:33]
	v_mfma_f32_16x16x32_bf16 v[22:25], v[162:165], v[218:221], v[22:25]
	v_mfma_f32_16x16x32_bf16 v[14:17], v[154:157], v[226:229], v[14:17]
	v_mfma_f32_16x16x32_bf16 v[6:9], v[162:165], v[226:229], v[6:9]
	v_mfma_f32_16x16x32_bf16 v[62:65], v[158:161], v[206:209], v[62:65]
	v_mfma_f32_16x16x32_bf16 v[54:57], v[166:169], v[206:209], v[54:57]
	v_mfma_f32_16x16x32_bf16 v[46:49], v[158:161], v[214:217], v[46:49]
	v_mfma_f32_16x16x32_bf16 v[38:41], v[166:169], v[214:217], v[38:41]
	v_mfma_f32_16x16x32_bf16 v[30:33], v[158:161], v[222:225], v[30:33]
	v_mfma_f32_16x16x32_bf16 v[22:25], v[166:169], v[222:225], v[22:25]
	v_mfma_f32_16x16x32_bf16 v[14:17], v[158:161], v[230:233], v[14:17]
	v_mfma_f32_16x16x32_bf16 v[6:9], v[166:169], v[230:233], v[6:9]
	s_setprio 0
	s_setprio 1
	v_mfma_f32_16x16x32_bf16 v[58:61], v[170:173], v[202:205], v[58:61]
	v_mfma_f32_16x16x32_bf16 v[50:53], v[182:185], v[202:205], v[50:53]
	v_mfma_f32_16x16x32_bf16 v[42:45], v[170:173], v[210:213], v[42:45]
	v_mfma_f32_16x16x32_bf16 v[34:37], v[182:185], v[210:213], v[34:37]
	v_mfma_f32_16x16x32_bf16 v[26:29], v[170:173], v[218:221], v[26:29]
	v_mfma_f32_16x16x32_bf16 v[18:21], v[182:185], v[218:221], v[18:21]
	v_mfma_f32_16x16x32_bf16 v[10:13], v[170:173], v[226:229], v[10:13]
	v_mfma_f32_16x16x32_bf16 v[2:5], v[182:185], v[226:229], v[2:5]
	v_mfma_f32_16x16x32_bf16 v[58:61], v[174:177], v[206:209], v[58:61]
	v_mfma_f32_16x16x32_bf16 v[50:53], v[198:201], v[206:209], v[50:53]
	v_mfma_f32_16x16x32_bf16 v[42:45], v[174:177], v[214:217], v[42:45]
	v_mfma_f32_16x16x32_bf16 v[34:37], v[198:201], v[214:217], v[34:37]
	v_mfma_f32_16x16x32_bf16 v[26:29], v[174:177], v[222:225], v[26:29]
	v_mfma_f32_16x16x32_bf16 v[18:21], v[198:201], v[222:225], v[18:21]
	v_mfma_f32_16x16x32_bf16 v[10:13], v[174:177], v[230:233], v[10:13]
	v_mfma_f32_16x16x32_bf16 v[2:5], v[198:201], v[230:233], v[2:5]
	s_setprio 0
	s_barrier
	v_add_u32_e32 v166, 0x18000, v143
	v_add_u32_e32 v186, 0x1c000, v143
	ds_read_b128 v[154:157], v166
	ds_read_b128 v[158:161], v166 offset:1024
	ds_read_b128 v[162:165], v166 offset:2048
	ds_read_b128 v[166:169], v166 offset:3072
	ds_read_b128 v[170:173], v186
	ds_read_b128 v[174:177], v186 offset:1024
	ds_read_b128 v[182:185], v186 offset:2048
	ds_read_b128 v[198:201], v186 offset:3072
	s_add_i32 s21, 0, 0x18000
	s_add_i32 s22, 0, 0x1c000
	s_add_u32 s18, s18, s28
	s_addc_u32 s19, s19, 0
	s_mov_b32 m0, s70
	v_lshl_add_u64 v[244:245], s[18:19], 0, v[134:135]
	ds_read_b128 v[202:205], v146 offset:32768
	ds_read_b128 v[206:209], v146 offset:33792
	ds_read_b128 v[210:213], v146 offset:34816
	ds_read_b128 v[214:217], v146 offset:35840
	ds_read_b128 v[218:221], v146 offset:36864
	ds_read_b128 v[222:225], v146 offset:37888
	ds_read_b128 v[226:229], v146 offset:38912
	ds_read_b128 v[230:233], v146 offset:39936
	global_load_lds_dwordx4 v[244:245], off
	v_lshl_add_u64 v[244:245], s[18:19], 0, v[132:133]
	s_mov_b32 m0, s71
	s_nop 0
	global_load_lds_dwordx4 v[244:245], off
	s_waitcnt vmcnt(8)
	s_waitcnt lgkmcnt(0)
	s_barrier
	s_setprio 1
	s_waitcnt lgkmcnt(0)
	v_mfma_f32_16x16x32_bf16 v[126:129], v[154:157], v[202:205], v[126:129]
	v_mfma_f32_16x16x32_bf16 v[118:121], v[162:165], v[202:205], v[118:121]
	v_mfma_f32_16x16x32_bf16 v[110:113], v[154:157], v[210:213], v[110:113]
	v_mfma_f32_16x16x32_bf16 v[102:105], v[162:165], v[210:213], v[102:105]
	v_mfma_f32_16x16x32_bf16 v[94:97], v[154:157], v[218:221], v[94:97]
	v_mfma_f32_16x16x32_bf16 v[86:89], v[162:165], v[218:221], v[86:89]
	v_mfma_f32_16x16x32_bf16 v[78:81], v[154:157], v[226:229], v[78:81]
	v_mfma_f32_16x16x32_bf16 v[70:73], v[162:165], v[226:229], v[70:73]
	v_mfma_f32_16x16x32_bf16 v[126:129], v[158:161], v[206:209], v[126:129]
	v_mfma_f32_16x16x32_bf16 v[118:121], v[166:169], v[206:209], v[118:121]
	v_mfma_f32_16x16x32_bf16 v[110:113], v[158:161], v[214:217], v[110:113]
	v_mfma_f32_16x16x32_bf16 v[102:105], v[166:169], v[214:217], v[102:105]
	v_mfma_f32_16x16x32_bf16 v[94:97], v[158:161], v[222:225], v[94:97]
	v_mfma_f32_16x16x32_bf16 v[86:89], v[166:169], v[222:225], v[86:89]
	v_mfma_f32_16x16x32_bf16 v[78:81], v[158:161], v[230:233], v[78:81]
	v_mfma_f32_16x16x32_bf16 v[70:73], v[166:169], v[230:233], v[70:73]
	s_setprio 0
	s_setprio 1
	v_mfma_f32_16x16x32_bf16 v[122:125], v[170:173], v[202:205], v[122:125]
	v_mfma_f32_16x16x32_bf16 v[114:117], v[182:185], v[202:205], v[114:117]
	v_mfma_f32_16x16x32_bf16 v[106:109], v[170:173], v[210:213], v[106:109]
	v_mfma_f32_16x16x32_bf16 v[98:101], v[182:185], v[210:213], v[98:101]
	v_mfma_f32_16x16x32_bf16 v[90:93], v[170:173], v[218:221], v[90:93]
	v_mfma_f32_16x16x32_bf16 v[82:85], v[182:185], v[218:221], v[82:85]
	v_mfma_f32_16x16x32_bf16 v[74:77], v[170:173], v[226:229], v[74:77]
	v_mfma_f32_16x16x32_bf16 v[66:69], v[182:185], v[226:229], v[66:69]
	v_mfma_f32_16x16x32_bf16 v[122:125], v[174:177], v[206:209], v[122:125]
	v_mfma_f32_16x16x32_bf16 v[114:117], v[198:201], v[206:209], v[114:117]
	v_mfma_f32_16x16x32_bf16 v[106:109], v[174:177], v[214:217], v[106:109]
	v_mfma_f32_16x16x32_bf16 v[98:101], v[198:201], v[214:217], v[98:101]
	v_mfma_f32_16x16x32_bf16 v[90:93], v[174:177], v[222:225], v[90:93]
	v_mfma_f32_16x16x32_bf16 v[82:85], v[198:201], v[222:225], v[82:85]
	v_mfma_f32_16x16x32_bf16 v[74:77], v[174:177], v[230:233], v[74:77]
	v_mfma_f32_16x16x32_bf16 v[66:69], v[198:201], v[230:233], v[66:69]
	s_setprio 0
	s_barrier
; #define PG8_STAGE(bufoff, gbase, voff) do { _Pragma("unroll") for (int _i = 0; _i < 2; ++_i) \
;         __builtin_amdgcn_global_load_lds((const unsigned*)((const char*)(gbase) + (voff)[_i]), (PG8_LAS unsigned*)(lds + (bufoff) + ldsw + _i * 8192), 16, 0, 0); } while (0)
; #define PG8_LDA(dst, b, h) do { _Pragma("unroll") for (int m = 0; m < 4; ++m) _Pragma("unroll") for (int k = 0; k < 2; ++k) dst[m][k] = *(const PG8_LAS bf16x8*)(lds + PG8_SA(b, h) + aoff + m * 2048 + k * 1024); } while (0)
; #define PG8_MMA(ai, bj, At, Bt) do { __builtin_amdgcn_s_setprio(1); _Pragma("unroll") for (int m = 0; m < 4; ++m) _Pragma("unroll") for (int n = 0; n < 2; ++n) _Pragma("unroll") for (int k = 0; k < 2; ++k) \
;         acc[ai][bj][m][n] = __builtin_amdgcn_mfma_f32_16x16x32_bf16(Bt[n][k], At[m][k], acc[ai][bj][m][n], 0, 0, 0); __builtin_amdgcn_s_setprio(0); } while (0)
; #define PG8_WAIT_V(n) asm volatile("s_waitcnt vmcnt(" #n ")" ::: "memory")
; #define PG8_WAIT_L(n) asm volatile("s_waitcnt lgkmcnt(" #n ")" ::: "memory")
; #define PG8_BAR __builtin_amdgcn_s_barrier()
; #define PG8_SCHED __builtin_amdgcn_sched_barrier(0)
; template <class Epi, class Sched, bool ALIGN_EPI = false, bool SP2 = false>
; __device__ __forceinline__ void gemm_phase(PG8_LAS unsigned char* lds, const Gemm g, const Sched S, const Epi E) {
;     ...
;             PG8_LDA(At, 1, 1); PG8_STAGE(PG8_SB(1, 0), b3, voffB); PG8_STAGE(PG8_SB(1, 1), b3 + hstep, voffB); PG8_STAGE(PG8_SA(1, 0), a3, voffA);
;             PG8_WAIT_V(8); PG8_WAIT_L(0); PG8_BAR; PG8_MMA(1, 0, At, B0); PG8_MMA(1, 1, At, B1); PG8_BAR; PG8_SCHED;
	s_add_i32 s18, s21, s61
	v_lshl_add_u64 v[140:141], v[140:141], 0, s[12:13]
	s_mov_b32 m0, s18
	ds_read_b128 v[202:205], v146 offset:49152
	ds_read_b128 v[206:209], v146 offset:50176
	ds_read_b128 v[210:213], v146 offset:51200
	ds_read_b128 v[214:217], v146 offset:52224
	ds_read_b128 v[218:221], v146 offset:53248
	ds_read_b128 v[222:225], v146 offset:54272
	ds_read_b128 v[226:229], v146 offset:55296
	ds_read_b128 v[230:233], v146 offset:56320
	global_load_lds_dwordx4 v[140:141], off
	v_lshl_add_u64 v[140:141], v[234:235], 0, s[12:13]
	s_add_i32 m0, s18, 0x2000
	s_add_i32 s18, s22, s61
	global_load_lds_dwordx4 v[140:141], off
	v_lshl_add_u64 v[140:141], v[236:237], 0, s[12:13]
	s_mov_b32 m0, s18
	s_nop 0
	global_load_lds_dwordx4 v[140:141], off
	v_lshl_add_u64 v[140:141], v[238:239], 0, s[12:13]
	s_add_i32 m0, s18, 0x2000
	s_nop 0
	global_load_lds_dwordx4 v[140:141], off
	v_lshl_add_u64 v[140:141], v[240:241], 0, s[12:13]
	s_mov_b32 m0, s73
	s_nop 0
	global_load_lds_dwordx4 v[140:141], off
	v_lshl_add_u64 v[140:141], v[242:243], 0, s[12:13]
	s_mov_b32 m0, s74
	s_nop 0
	global_load_lds_dwordx4 v[140:141], off
	s_waitcnt vmcnt(8)
	s_waitcnt lgkmcnt(0)
	s_barrier
	s_setprio 1
	s_waitcnt lgkmcnt(0)
	v_mfma_f32_16x16x32_bf16 v[62:65], v[154:157], v[202:205], v[62:65]
	v_mfma_f32_16x16x32_bf16 v[54:57], v[162:165], v[202:205], v[54:57]
	v_mfma_f32_16x16x32_bf16 v[46:49], v[154:157], v[210:213], v[46:49]
	v_mfma_f32_16x16x32_bf16 v[38:41], v[162:165], v[210:213], v[38:41]
	v_mfma_f32_16x16x32_bf16 v[30:33], v[154:157], v[218:221], v[30:33]
	v_mfma_f32_16x16x32_bf16 v[22:25], v[162:165], v[218:221], v[22:25]
	v_mfma_f32_16x16x32_bf16 v[14:17], v[154:157], v[226:229], v[14:17]
	v_mfma_f32_16x16x32_bf16 v[6:9], v[162:165], v[226:229], v[6:9]
	v_mfma_f32_16x16x32_bf16 v[62:65], v[158:161], v[206:209], v[62:65]
	v_mfma_f32_16x16x32_bf16 v[54:57], v[166:169], v[206:209], v[54:57]
	v_mfma_f32_16x16x32_bf16 v[46:49], v[158:161], v[214:217], v[46:49]
	v_mfma_f32_16x16x32_bf16 v[38:41], v[166:169], v[214:217], v[38:41]
	v_mfma_f32_16x16x32_bf16 v[30:33], v[158:161], v[222:225], v[30:33]
	v_mfma_f32_16x16x32_bf16 v[22:25], v[166:169], v[222:225], v[22:25]
	v_mfma_f32_16x16x32_bf16 v[14:17], v[158:161], v[230:233], v[14:17]
	v_mfma_f32_16x16x32_bf16 v[6:9], v[166:169], v[230:233], v[6:9]
	s_setprio 0
	s_setprio 1
	v_mfma_f32_16x16x32_bf16 v[58:61], v[170:173], v[202:205], v[58:61]
	v_mfma_f32_16x16x32_bf16 v[50:53], v[182:185], v[202:205], v[50:53]
	v_mfma_f32_16x16x32_bf16 v[42:45], v[170:173], v[210:213], v[42:45]
	v_mfma_f32_16x16x32_bf16 v[34:37], v[182:185], v[210:213], v[34:37]
	v_mfma_f32_16x16x32_bf16 v[26:29], v[170:173], v[218:221], v[26:29]
	v_mfma_f32_16x16x32_bf16 v[18:21], v[182:185], v[218:221], v[18:21]
	v_mfma_f32_16x16x32_bf16 v[10:13], v[170:173], v[226:229], v[10:13]
	v_mfma_f32_16x16x32_bf16 v[2:5], v[182:185], v[226:229], v[2:5]
	v_mfma_f32_16x16x32_bf16 v[58:61], v[174:177], v[206:209], v[58:61]
	v_mfma_f32_16x16x32_bf16 v[50:53], v[198:201], v[206:209], v[50:53]
	v_mfma_f32_16x16x32_bf16 v[42:45], v[174:177], v[214:217], v[42:45]
	v_mfma_f32_16x16x32_bf16 v[34:37], v[198:201], v[214:217], v[34:37]
	v_mfma_f32_16x16x32_bf16 v[26:29], v[174:177], v[222:225], v[26:29]
	v_mfma_f32_16x16x32_bf16 v[18:21], v[198:201], v[222:225], v[18:21]
	v_mfma_f32_16x16x32_bf16 v[10:13], v[174:177], v[230:233], v[10:13]
	v_mfma_f32_16x16x32_bf16 v[2:5], v[198:201], v[230:233], v[2:5]
	s_setprio 0
	s_add_u32 s16, s16, 0x100
	s_addc_u32 s17, s17, 0
	s_add_u32 s14, s14, 0x100
	s_addc_u32 s15, s15, 0
	s_cmp_ge_u32 s20, s72
	s_mov_b32 s18, s20
	s_barrier
	s_cbranch_scc0 .LBB0_180
	s_and_b64 vcc, exec, s[56:57]
	s_cbranch_vccz .LBB0_183
	s_barrier

; #define PG8_STAGE(bufoff, gbase, voff) do { _Pragma("unroll") for (int _i = 0; _i < 2; ++_i) \
;         __builtin_amdgcn_global_load_lds((const unsigned*)((const char*)(gbase) + (voff)[_i]), (PG8_LAS unsigned*)(lds + (bufoff) + ldsw + _i * 8192), 16, 0, 0); } while (0)
; #define PG8_LDA(dst, b, h) do { _Pragma("unroll") for (int m = 0; m < 4; ++m) _Pragma("unroll") for (int k = 0; k < 2; ++k) dst[m][k] = *(const PG8_LAS bf16x8*)(lds + PG8_SA(b, h) + aoff + m * 2048 + k * 1024); } while (0)
; #define PG8_LDB(dst, b, h) do { _Pragma("unroll") for (int n = 0; n < 2; ++n) _Pragma("unroll") for (int k = 0; k < 2; ++k) dst[n][k] = *(const PG8_LAS bf16x8*)(lds + PG8_SB(b, h) + boff + n * 2048 + k * 1024); } while (0)
; #define PG8_MMA(ai, bj, At, Bt) do { __builtin_amdgcn_s_setprio(1); _Pragma("unroll") for (int m = 0; m < 4; ++m) _Pragma("unroll") for (int n = 0; n < 2; ++n) _Pragma("unroll") for (int k = 0; k < 2; ++k) \
;         acc[ai][bj][m][n] = __builtin_amdgcn_mfma_f32_16x16x32_bf16(Bt[n][k], At[m][k], acc[ai][bj][m][n], 0, 0, 0); __builtin_amdgcn_s_setprio(0); } while (0)
; #define PG8_WAIT_V(n) asm volatile("s_waitcnt vmcnt(" #n ")" ::: "memory")
; #define PG8_WAIT_L(n) asm volatile("s_waitcnt lgkmcnt(" #n ")" ::: "memory")
; #define PG8_BAR __builtin_amdgcn_s_barrier()
; #define PG8_SCHED __builtin_amdgcn_sched_barrier(0)
; template <class Epi, class Sched, bool ALIGN_EPI = false, bool SP2 = false>
; __device__ __forceinline__ void gemm_phase(PG8_LAS unsigned char* lds, const Gemm g, const Sched S, const Epi E) {
;     ...
;             const bool last = (t == nt - 2);
;             const char* a1 = cA + (size_t)(t + 1) * kstep;
;             const char* a2 = last ? nA : cA + (size_t)(t + 2) * kstep; const char* b2 = last ? nB : cB + (size_t)(t + 2) * kstep;
;             const char* a3 = a2 + kstep; const char* b3 = b2 + kstep;
;             if (last && has_next) S.a_ready(nxt);
;             if constexpr (SP2) {
;             PG8_LDB(B0, 0, 0); PG8_LDB(B1, 0, 1); PG8_SCHED; PG8_LDA(At, 0, 0); PG8_STAGE(PG8_SA(1, 1), a1 + hstep, voffA);
;             PG8_WAIT_V(8); PG8_WAIT_L(0); PG8_BAR; PG8_MMA(0, 0, At, B0); PG8_MMA(0, 1, At, B1); PG8_BAR; PG8_SCHED;
;             PG8_LDA(At, 0, 1); PG8_STAGE(PG8_SB(0, 0), b2, voffB); PG8_STAGE(PG8_SB(0, 1), b2 + hstep, voffB); PG8_STAGE(PG8_SA(0, 0), a2, voffA);
.LBB0_224:
	v_add_u32_e32 v141, 0x10000, v147
	ds_read_b128 v[154:157], v141
	ds_read_b128 v[158:161], v141 offset:1024
	ds_read_b128 v[162:165], v141 offset:2048
	ds_read_b128 v[166:169], v141 offset:3072
	v_add_u32_e32 v141, 0x14000, v147
	ds_read_b128 v[170:173], v141
	ds_read_b128 v[174:177], v141 offset:1024
	ds_read_b128 v[182:185], v141 offset:2048
	ds_read_b128 v[198:201], v141 offset:3072
	s_add_i32 s21, s20, 2
	s_add_u32 s22, s30, 0x80
	s_addc_u32 s23, s31, 0
	s_add_i32 s26, 0, 0x10000
	s_cmp_eq_u32 s81, s20
	s_cselect_b32 s75, s1, s23
	s_cselect_b32 s74, s0, s22
	s_cselect_b32 s23, s19, s15
	s_cselect_b32 s22, s18, s14
	s_add_i32 s20, 0, 0x14000
	v_lshl_add_u64 v[234:235], s[30:31], 0, v[136:137]
	s_add_i32 m0, s85, 0xc000
	ds_read_b128 v[202:205], v152
	ds_read_b128 v[206:209], v152 offset:1024
	ds_read_b128 v[210:213], v152 offset:2048
	ds_read_b128 v[214:217], v152 offset:3072
	ds_read_b128 v[218:221], v152 offset:4096
	ds_read_b128 v[222:225], v152 offset:5120
	ds_read_b128 v[226:229], v152 offset:6144
	ds_read_b128 v[230:233], v152 offset:7168
	global_load_lds_dwordx4 v[234:235], off
	v_lshl_add_u64 v[234:235], s[30:31], 0, v[138:139]
	s_add_i32 m0, s85, 0xe000
	s_nop 0
	global_load_lds_dwordx4 v[234:235], off
	s_waitcnt vmcnt(8)
	s_waitcnt lgkmcnt(0)
	s_barrier
	s_setprio 1
	s_waitcnt lgkmcnt(0)
	v_mfma_f32_16x16x32_bf16 v[126:129], v[154:157], v[202:205], v[126:129]
	v_mfma_f32_16x16x32_bf16 v[122:125], v[162:165], v[202:205], v[122:125]
	v_mfma_f32_16x16x32_bf16 v[110:113], v[154:157], v[210:213], v[110:113]
	v_mfma_f32_16x16x32_bf16 v[106:109], v[162:165], v[210:213], v[106:109]
	v_mfma_f32_16x16x32_bf16 v[94:97], v[154:157], v[218:221], v[94:97]
	v_mfma_f32_16x16x32_bf16 v[90:93], v[162:165], v[218:221], v[90:93]
	v_mfma_f32_16x16x32_bf16 v[78:81], v[154:157], v[226:229], v[78:81]
	v_mfma_f32_16x16x32_bf16 v[74:77], v[162:165], v[226:229], v[74:77]
	v_mfma_f32_16x16x32_bf16 v[126:129], v[158:161], v[206:209], v[126:129]
	v_mfma_f32_16x16x32_bf16 v[122:125], v[166:169], v[206:209], v[122:125]
	v_mfma_f32_16x16x32_bf16 v[110:113], v[158:161], v[214:217], v[110:113]
	v_mfma_f32_16x16x32_bf16 v[106:109], v[166:169], v[214:217], v[106:109]
	v_mfma_f32_16x16x32_bf16 v[94:97], v[158:161], v[222:225], v[94:97]
	v_mfma_f32_16x16x32_bf16 v[90:93], v[166:169], v[222:225], v[90:93]
	v_mfma_f32_16x16x32_bf16 v[78:81], v[158:161], v[230:233], v[78:81]
	v_mfma_f32_16x16x32_bf16 v[74:77], v[166:169], v[230:233], v[74:77]
	s_setprio 0
	s_setprio 1
	v_mfma_f32_16x16x32_bf16 v[118:121], v[170:173], v[202:205], v[118:121]
	v_mfma_f32_16x16x32_bf16 v[114:117], v[182:185], v[202:205], v[114:117]
	v_mfma_f32_16x16x32_bf16 v[102:105], v[170:173], v[210:213], v[102:105]
	v_mfma_f32_16x16x32_bf16 v[98:101], v[182:185], v[210:213], v[98:101]
	v_mfma_f32_16x16x32_bf16 v[86:89], v[170:173], v[218:221], v[86:89]
	v_mfma_f32_16x16x32_bf16 v[82:85], v[182:185], v[218:221], v[82:85]
	v_mfma_f32_16x16x32_bf16 v[70:73], v[170:173], v[226:229], v[70:73]
	v_mfma_f32_16x16x32_bf16 v[66:69], v[182:185], v[226:229], v[66:69]
	v_mfma_f32_16x16x32_bf16 v[118:121], v[174:177], v[206:209], v[118:121]
	v_mfma_f32_16x16x32_bf16 v[114:117], v[198:201], v[206:209], v[114:117]
	v_mfma_f32_16x16x32_bf16 v[102:105], v[174:177], v[214:217], v[102:105]
	v_mfma_f32_16x16x32_bf16 v[98:101], v[198:201], v[214:217], v[98:101]
	v_mfma_f32_16x16x32_bf16 v[86:89], v[174:177], v[222:225], v[86:89]
	v_mfma_f32_16x16x32_bf16 v[82:85], v[198:201], v[222:225], v[82:85]
	v_mfma_f32_16x16x32_bf16 v[70:73], v[174:177], v[230:233], v[70:73]
	v_mfma_f32_16x16x32_bf16 v[66:69], v[198:201], v[230:233], v[66:69]
	s_setprio 0
	s_barrier
	s_add_i32 s26, s26, s84
	v_lshl_add_u64 v[234:235], s[22:23], 0, v[0:1]
	s_mov_b32 m0, s26
	ds_read_b128 v[202:205], v152 offset:16384
	ds_read_b128 v[206:209], v152 offset:17408
	ds_read_b128 v[210:213], v152 offset:18432
	ds_read_b128 v[214:217], v152 offset:19456
	ds_read_b128 v[218:221], v152 offset:20480
	ds_read_b128 v[222:225], v152 offset:21504
	ds_read_b128 v[226:229], v152 offset:22528
	ds_read_b128 v[230:233], v152 offset:23552
	global_load_lds_dwordx4 v[234:235], off
	s_add_i32 m0, s26, 0x2000
	v_lshl_add_u64 v[236:237], s[22:23], 0, v[134:135]
	s_add_u32 s22, s22, s52
	s_addc_u32 s23, s23, 0
	s_add_i32 s20, s20, s84
	global_load_lds_dwordx4 v[236:237], off
	v_lshl_add_u64 v[238:239], s[22:23], 0, v[0:1]
	s_mov_b32 m0, s20
	v_lshl_add_u64 v[240:241], s[22:23], 0, v[134:135]
	global_load_lds_dwordx4 v[238:239], off
	s_add_i32 m0, s20, 0x2000
	v_lshl_add_u64 v[242:243], s[74:75], 0, v[130:131]
	global_load_lds_dwordx4 v[240:241], off
	s_mov_b32 m0, s85
	v_lshl_add_u64 v[244:245], s[74:75], 0, v[132:133]
	global_load_lds_dwordx4 v[242:243], off
	s_mov_b32 m0, s86
	s_nop 0
	global_load_lds_dwordx4 v[244:245], off
	s_waitcnt vmcnt(8)
	s_waitcnt lgkmcnt(0)
	s_barrier
; #define PG8_STAGE(bufoff, gbase, voff) do { _Pragma("unroll") for (int _i = 0; _i < 2; ++_i) \
;         __builtin_amdgcn_global_load_lds((const unsigned*)((const char*)(gbase) + (voff)[_i]), (PG8_LAS unsigned*)(lds + (bufoff) + ldsw + _i * 8192), 16, 0, 0); } while (0)
; #define PG8_LDA(dst, b, h) do { _Pragma("unroll") for (int m = 0; m < 4; ++m) _Pragma("unroll") for (int k = 0; k < 2; ++k) dst[m][k] = *(const PG8_LAS bf16x8*)(lds + PG8_SA(b, h) + aoff + m * 2048 + k * 1024); } while (0)
; #define PG8_LDB(dst, b, h) do { _Pragma("unroll") for (int n = 0; n < 2; ++n) _Pragma("unroll") for (int k = 0; k < 2; ++k) dst[n][k] = *(const PG8_LAS bf16x8*)(lds + PG8_SB(b, h) + boff + n * 2048 + k * 1024); } while (0)
; #define PG8_MMA(ai, bj, At, Bt) do { __builtin_amdgcn_s_setprio(1); _Pragma("unroll") for (int m = 0; m < 4; ++m) _Pragma("unroll") for (int n = 0; n < 2; ++n) _Pragma("unroll") for (int k = 0; k < 2; ++k) \
;         acc[ai][bj][m][n] = __builtin_amdgcn_mfma_f32_16x16x32_bf16(Bt[n][k], At[m][k], acc[ai][bj][m][n], 0, 0, 0); __builtin_amdgcn_s_setprio(0); } while (0)
; #define PG8_WAIT_V(n) asm volatile("s_waitcnt vmcnt(" #n ")" ::: "memory")
; #define PG8_WAIT_L(n) asm volatile("s_waitcnt lgkmcnt(" #n ")" ::: "memory")
; #define PG8_BAR __builtin_amdgcn_s_barrier()
; #define PG8_SCHED __builtin_amdgcn_sched_barrier(0)
; template <class Epi, class Sched, bool ALIGN_EPI = false, bool SP2 = false>
; __device__ __forceinline__ void gemm_phase(PG8_LAS unsigned char* lds, const Gemm g, const Sched S, const Epi E) {
;     ...
;             PG8_WAIT_V(8); PG8_WAIT_L(0); PG8_BAR; PG8_MMA(1, 0, At, B0); PG8_MMA(1, 1, At, B1); PG8_BAR; PG8_SCHED;
;             PG8_LDB(B0, 1, 0); PG8_LDB(B1, 1, 1); PG8_SCHED; PG8_LDA(At, 1, 0); PG8_STAGE(PG8_SA(0, 1), a2 + hstep, voffA);
;             PG8_WAIT_V(8); PG8_WAIT_L(0); PG8_BAR; PG8_MMA(0, 0, At, B0); PG8_MMA(0, 1, At, B1); PG8_BAR; PG8_SCHED;
	s_setprio 1
	s_waitcnt lgkmcnt(0)
	v_mfma_f32_16x16x32_bf16 v[62:65], v[154:157], v[202:205], v[62:65]
	v_mfma_f32_16x16x32_bf16 v[58:61], v[162:165], v[202:205], v[58:61]
	v_mfma_f32_16x16x32_bf16 v[46:49], v[154:157], v[210:213], v[46:49]
	v_mfma_f32_16x16x32_bf16 v[42:45], v[162:165], v[210:213], v[42:45]
	v_mfma_f32_16x16x32_bf16 v[30:33], v[154:157], v[218:221], v[30:33]
	v_mfma_f32_16x16x32_bf16 v[26:29], v[162:165], v[218:221], v[26:29]
	v_mfma_f32_16x16x32_bf16 v[14:17], v[154:157], v[226:229], v[14:17]
	v_mfma_f32_16x16x32_bf16 v[10:13], v[162:165], v[226:229], v[10:13]
	v_mfma_f32_16x16x32_bf16 v[62:65], v[158:161], v[206:209], v[62:65]
	v_mfma_f32_16x16x32_bf16 v[58:61], v[166:169], v[206:209], v[58:61]
	v_mfma_f32_16x16x32_bf16 v[46:49], v[158:161], v[214:217], v[46:49]
	v_mfma_f32_16x16x32_bf16 v[42:45], v[166:169], v[214:217], v[42:45]
	v_mfma_f32_16x16x32_bf16 v[30:33], v[158:161], v[222:225], v[30:33]
	v_mfma_f32_16x16x32_bf16 v[26:29], v[166:169], v[222:225], v[26:29]
	v_mfma_f32_16x16x32_bf16 v[14:17], v[158:161], v[230:233], v[14:17]
	v_mfma_f32_16x16x32_bf16 v[10:13], v[166:169], v[230:233], v[10:13]
	s_setprio 0
	s_setprio 1
	v_mfma_f32_16x16x32_bf16 v[54:57], v[170:173], v[202:205], v[54:57]
	v_mfma_f32_16x16x32_bf16 v[50:53], v[182:185], v[202:205], v[50:53]
	v_mfma_f32_16x16x32_bf16 v[38:41], v[170:173], v[210:213], v[38:41]
	v_mfma_f32_16x16x32_bf16 v[34:37], v[182:185], v[210:213], v[34:37]
	v_mfma_f32_16x16x32_bf16 v[22:25], v[170:173], v[218:221], v[22:25]
	v_mfma_f32_16x16x32_bf16 v[18:21], v[182:185], v[218:221], v[18:21]
	v_mfma_f32_16x16x32_bf16 v[6:9], v[170:173], v[226:229], v[6:9]
	v_mfma_f32_16x16x32_bf16 v[2:5], v[182:185], v[226:229], v[2:5]
	v_mfma_f32_16x16x32_bf16 v[54:57], v[174:177], v[206:209], v[54:57]
	v_mfma_f32_16x16x32_bf16 v[50:53], v[198:201], v[206:209], v[50:53]
	v_mfma_f32_16x16x32_bf16 v[38:41], v[174:177], v[214:217], v[38:41]
	v_mfma_f32_16x16x32_bf16 v[34:37], v[198:201], v[214:217], v[34:37]
	v_mfma_f32_16x16x32_bf16 v[22:25], v[174:177], v[222:225], v[22:25]
	v_mfma_f32_16x16x32_bf16 v[18:21], v[198:201], v[222:225], v[18:21]
	v_mfma_f32_16x16x32_bf16 v[6:9], v[174:177], v[230:233], v[6:9]
	v_mfma_f32_16x16x32_bf16 v[2:5], v[198:201], v[230:233], v[2:5]
	s_setprio 0
	s_barrier
	v_add_u32_e32 v141, 0x18000, v147
	ds_read_b128 v[154:157], v141
	ds_read_b128 v[158:161], v141 offset:1024
	ds_read_b128 v[162:165], v141 offset:2048
	ds_read_b128 v[166:169], v141 offset:3072
	v_add_u32_e32 v141, 0x1c000, v147
	ds_read_b128 v[170:173], v141
	ds_read_b128 v[174:177], v141 offset:1024
	ds_read_b128 v[182:185], v141 offset:2048
	ds_read_b128 v[198:201], v141 offset:3072
	s_add_i32 s20, 0, 0x18000
	s_add_i32 s26, 0, 0x1c000
	s_add_u32 s22, s74, s52
	s_addc_u32 s23, s75, 0
	s_mov_b32 m0, s87
	v_lshl_add_u64 v[246:247], s[22:23], 0, v[130:131]
	ds_read_b128 v[202:205], v152 offset:32768
	ds_read_b128 v[206:209], v152 offset:33792
	ds_read_b128 v[210:213], v152 offset:34816
	ds_read_b128 v[214:217], v152 offset:35840
	ds_read_b128 v[218:221], v152 offset:36864
	ds_read_b128 v[222:225], v152 offset:37888
	ds_read_b128 v[226:229], v152 offset:38912
	ds_read_b128 v[230:233], v152 offset:39936
	global_load_lds_dwordx4 v[246:247], off
	v_lshl_add_u64 v[246:247], s[22:23], 0, v[132:133]
	s_mov_b32 m0, s88
	s_nop 0
	global_load_lds_dwordx4 v[246:247], off
	s_waitcnt vmcnt(8)
	s_waitcnt lgkmcnt(0)
	s_barrier
	s_setprio 1
	s_waitcnt lgkmcnt(0)
	v_mfma_f32_16x16x32_bf16 v[126:129], v[154:157], v[202:205], v[126:129]
	v_mfma_f32_16x16x32_bf16 v[122:125], v[162:165], v[202:205], v[122:125]
	v_mfma_f32_16x16x32_bf16 v[110:113], v[154:157], v[210:213], v[110:113]
	v_mfma_f32_16x16x32_bf16 v[106:109], v[162:165], v[210:213], v[106:109]
	v_mfma_f32_16x16x32_bf16 v[94:97], v[154:157], v[218:221], v[94:97]
	v_mfma_f32_16x16x32_bf16 v[90:93], v[162:165], v[218:221], v[90:93]
	v_mfma_f32_16x16x32_bf16 v[78:81], v[154:157], v[226:229], v[78:81]
	v_mfma_f32_16x16x32_bf16 v[74:77], v[162:165], v[226:229], v[74:77]
	v_mfma_f32_16x16x32_bf16 v[126:129], v[158:161], v[206:209], v[126:129]
	v_mfma_f32_16x16x32_bf16 v[122:125], v[166:169], v[206:209], v[122:125]
	v_mfma_f32_16x16x32_bf16 v[110:113], v[158:161], v[214:217], v[110:113]
	v_mfma_f32_16x16x32_bf16 v[106:109], v[166:169], v[214:217], v[106:109]
	v_mfma_f32_16x16x32_bf16 v[94:97], v[158:161], v[222:225], v[94:97]
	v_mfma_f32_16x16x32_bf16 v[90:93], v[166:169], v[222:225], v[90:93]
	v_mfma_f32_16x16x32_bf16 v[78:81], v[158:161], v[230:233], v[78:81]
	v_mfma_f32_16x16x32_bf16 v[74:77], v[166:169], v[230:233], v[74:77]
	s_setprio 0
	s_setprio 1
	v_mfma_f32_16x16x32_bf16 v[118:121], v[170:173], v[202:205], v[118:121]
	v_mfma_f32_16x16x32_bf16 v[114:117], v[182:185], v[202:205], v[114:117]
	v_mfma_f32_16x16x32_bf16 v[102:105], v[170:173], v[210:213], v[102:105]
	v_mfma_f32_16x16x32_bf16 v[98:101], v[182:185], v[210:213], v[98:101]
	v_mfma_f32_16x16x32_bf16 v[86:89], v[170:173], v[218:221], v[86:89]
	v_mfma_f32_16x16x32_bf16 v[82:85], v[182:185], v[218:221], v[82:85]
	v_mfma_f32_16x16x32_bf16 v[70:73], v[170:173], v[226:229], v[70:73]
	v_mfma_f32_16x16x32_bf16 v[66:69], v[182:185], v[226:229], v[66:69]
	v_mfma_f32_16x16x32_bf16 v[118:121], v[174:177], v[206:209], v[118:121]
	v_mfma_f32_16x16x32_bf16 v[114:117], v[198:201], v[206:209], v[114:117]
	v_mfma_f32_16x16x32_bf16 v[102:105], v[174:177], v[214:217], v[102:105]
	v_mfma_f32_16x16x32_bf16 v[98:101], v[198:201], v[214:217], v[98:101]
	v_mfma_f32_16x16x32_bf16 v[86:89], v[174:177], v[222:225], v[86:89]
	v_mfma_f32_16x16x32_bf16 v[82:85], v[198:201], v[222:225], v[82:85]
	v_mfma_f32_16x16x32_bf16 v[70:73], v[174:177], v[230:233], v[70:73]
	v_mfma_f32_16x16x32_bf16 v[66:69], v[198:201], v[230:233], v[66:69]
	s_setprio 0
	s_barrier
; #define PG8_STAGE(bufoff, gbase, voff) do { _Pragma("unroll") for (int _i = 0; _i < 2; ++_i) \
;         __builtin_amdgcn_global_load_lds((const unsigned*)((const char*)(gbase) + (voff)[_i]), (PG8_LAS unsigned*)(lds + (bufoff) + ldsw + _i * 8192), 16, 0, 0); } while (0)
; #define PG8_LDA(dst, b, h) do { _Pragma("unroll") for (int m = 0; m < 4; ++m) _Pragma("unroll") for (int k = 0; k < 2; ++k) dst[m][k] = *(const PG8_LAS bf16x8*)(lds + PG8_SA(b, h) + aoff + m * 2048 + k * 1024); } while (0)
; #define PG8_MMA(ai, bj, At, Bt) do { __builtin_amdgcn_s_setprio(1); _Pragma("unroll") for (int m = 0; m < 4; ++m) _Pragma("unroll") for (int n = 0; n < 2; ++n) _Pragma("unroll") for (int k = 0; k < 2; ++k) \
;         acc[ai][bj][m][n] = __builtin_amdgcn_mfma_f32_16x16x32_bf16(Bt[n][k], At[m][k], acc[ai][bj][m][n], 0, 0, 0); __builtin_amdgcn_s_setprio(0); } while (0)
; #define PG8_WAIT_V(n) asm volatile("s_waitcnt vmcnt(" #n ")" ::: "memory")
; #define PG8_WAIT_L(n) asm volatile("s_waitcnt lgkmcnt(" #n ")" ::: "memory")
; #define PG8_BAR __builtin_amdgcn_s_barrier()
; #define PG8_SCHED __builtin_amdgcn_sched_barrier(0)
; template <class Epi, class Sched, bool ALIGN_EPI = false, bool SP2 = false>
; __device__ __forceinline__ void gemm_phase(PG8_LAS unsigned char* lds, const Gemm g, const Sched S, const Epi E) {
;     ...
;             PG8_LDA(At, 1, 1); PG8_STAGE(PG8_SB(1, 0), b3, voffB); PG8_STAGE(PG8_SB(1, 1), b3 + hstep, voffB); PG8_STAGE(PG8_SA(1, 0), a3, voffA);
;             PG8_WAIT_V(8); PG8_WAIT_L(0); PG8_BAR; PG8_MMA(1, 0, At, B0); PG8_MMA(1, 1, At, B1); PG8_BAR; PG8_SCHED;
	s_add_i32 s20, s20, s84
	v_lshl_add_u64 v[234:235], v[234:235], 0, s[12:13]
	s_mov_b32 m0, s20
	ds_read_b128 v[202:205], v152 offset:49152
	ds_read_b128 v[206:209], v152 offset:50176
	ds_read_b128 v[210:213], v152 offset:51200
	ds_read_b128 v[214:217], v152 offset:52224
	ds_read_b128 v[218:221], v152 offset:53248
	ds_read_b128 v[222:225], v152 offset:54272
	ds_read_b128 v[226:229], v152 offset:55296
	ds_read_b128 v[230:233], v152 offset:56320
	global_load_lds_dwordx4 v[234:235], off
	v_lshl_add_u64 v[234:235], v[236:237], 0, s[12:13]
	s_add_i32 m0, s20, 0x2000
	s_add_i32 s20, s26, s84
	global_load_lds_dwordx4 v[234:235], off
	v_lshl_add_u64 v[234:235], v[238:239], 0, s[12:13]
	s_mov_b32 m0, s20
	s_nop 0
	global_load_lds_dwordx4 v[234:235], off
	v_lshl_add_u64 v[234:235], v[240:241], 0, s[12:13]
	s_add_i32 m0, s20, 0x2000
	s_nop 0
	global_load_lds_dwordx4 v[234:235], off
	v_lshl_add_u64 v[234:235], v[242:243], 0, s[12:13]
	s_mov_b32 m0, s3
	s_nop 0
	global_load_lds_dwordx4 v[234:235], off
	v_lshl_add_u64 v[234:235], v[244:245], 0, s[12:13]
	s_mov_b32 m0, s24
	s_nop 0
	global_load_lds_dwordx4 v[234:235], off
	s_waitcnt vmcnt(8)
	s_waitcnt lgkmcnt(0)
	s_barrier
	s_setprio 1
	s_waitcnt lgkmcnt(0)
	v_mfma_f32_16x16x32_bf16 v[62:65], v[154:157], v[202:205], v[62:65]
	v_mfma_f32_16x16x32_bf16 v[58:61], v[162:165], v[202:205], v[58:61]
	v_mfma_f32_16x16x32_bf16 v[46:49], v[154:157], v[210:213], v[46:49]
	v_mfma_f32_16x16x32_bf16 v[42:45], v[162:165], v[210:213], v[42:45]
	v_mfma_f32_16x16x32_bf16 v[30:33], v[154:157], v[218:221], v[30:33]
	v_mfma_f32_16x16x32_bf16 v[26:29], v[162:165], v[218:221], v[26:29]
	v_mfma_f32_16x16x32_bf16 v[14:17], v[154:157], v[226:229], v[14:17]
	v_mfma_f32_16x16x32_bf16 v[10:13], v[162:165], v[226:229], v[10:13]
	v_mfma_f32_16x16x32_bf16 v[62:65], v[158:161], v[206:209], v[62:65]
	v_mfma_f32_16x16x32_bf16 v[58:61], v[166:169], v[206:209], v[58:61]
	v_mfma_f32_16x16x32_bf16 v[46:49], v[158:161], v[214:217], v[46:49]
	v_mfma_f32_16x16x32_bf16 v[42:45], v[166:169], v[214:217], v[42:45]
	v_mfma_f32_16x16x32_bf16 v[30:33], v[158:161], v[222:225], v[30:33]
	v_mfma_f32_16x16x32_bf16 v[26:29], v[166:169], v[222:225], v[26:29]
	v_mfma_f32_16x16x32_bf16 v[14:17], v[158:161], v[230:233], v[14:17]
	v_mfma_f32_16x16x32_bf16 v[10:13], v[166:169], v[230:233], v[10:13]
	s_setprio 0
	s_setprio 1
	v_mfma_f32_16x16x32_bf16 v[54:57], v[170:173], v[202:205], v[54:57]
	v_mfma_f32_16x16x32_bf16 v[50:53], v[182:185], v[202:205], v[50:53]
	v_mfma_f32_16x16x32_bf16 v[38:41], v[170:173], v[210:213], v[38:41]
	v_mfma_f32_16x16x32_bf16 v[34:37], v[182:185], v[210:213], v[34:37]
	v_mfma_f32_16x16x32_bf16 v[22:25], v[170:173], v[218:221], v[22:25]
	v_mfma_f32_16x16x32_bf16 v[18:21], v[182:185], v[218:221], v[18:21]
	v_mfma_f32_16x16x32_bf16 v[6:9], v[170:173], v[226:229], v[6:9]
	v_mfma_f32_16x16x32_bf16 v[2:5], v[182:185], v[226:229], v[2:5]
	v_mfma_f32_16x16x32_bf16 v[54:57], v[174:177], v[206:209], v[54:57]
	v_mfma_f32_16x16x32_bf16 v[50:53], v[198:201], v[206:209], v[50:53]
	v_mfma_f32_16x16x32_bf16 v[38:41], v[174:177], v[214:217], v[38:41]
	v_mfma_f32_16x16x32_bf16 v[34:37], v[198:201], v[214:217], v[34:37]
	v_mfma_f32_16x16x32_bf16 v[22:25], v[174:177], v[222:225], v[22:25]
	v_mfma_f32_16x16x32_bf16 v[18:21], v[198:201], v[222:225], v[18:21]
	v_mfma_f32_16x16x32_bf16 v[6:9], v[174:177], v[230:233], v[6:9]
	v_mfma_f32_16x16x32_bf16 v[2:5], v[198:201], v[230:233], v[2:5]
	s_setprio 0
	s_add_u32 s30, s30, 0x100
	s_addc_u32 s31, s31, 0
	s_add_u32 s14, s14, 0x100
	s_addc_u32 s15, s15, 0
	s_cmp_ge_u32 s21, s80
	s_mov_b32 s20, s21
	s_barrier
	s_cbranch_scc0 .LBB0_224
	s_and_b64 vcc, exec, s[16:17]
	s_cbranch_vccz .LBB0_227
	s_barrier

; #define PG8_STAGE(bufoff, gbase, voff) do { _Pragma("unroll") for (int _i = 0; _i < 2; ++_i) \
;         __builtin_amdgcn_global_load_lds((const unsigned*)((const char*)(gbase) + (voff)[_i]), (PG8_LAS unsigned*)(lds + (bufoff) + ldsw + _i * 8192), 16, 0, 0); } while (0)
; #define PG8_LDA(dst, b, h) do { _Pragma("unroll") for (int m = 0; m < 4; ++m) _Pragma("unroll") for (int k = 0; k < 2; ++k) dst[m][k] = *(const PG8_LAS bf16x8*)(lds + PG8_SA(b, h) + aoff + m * 2048 + k * 1024); } while (0)
; #define PG8_LDB(dst, b, h) do { _Pragma("unroll") for (int n = 0; n < 2; ++n) _Pragma("unroll") for (int k = 0; k < 2; ++k) dst[n][k] = *(const PG8_LAS bf16x8*)(lds + PG8_SB(b, h) + boff + n * 2048 + k * 1024); } while (0)
; #define PG8_MMA(ai, bj, At, Bt) do { __builtin_amdgcn_s_setprio(1); _Pragma("unroll") for (int m = 0; m < 4; ++m) _Pragma("unroll") for (int n = 0; n < 2; ++n) _Pragma("unroll") for (int k = 0; k < 2; ++k) \
;         acc[ai][bj][m][n] = __builtin_amdgcn_mfma_f32_16x16x32_bf16(Bt[n][k], At[m][k], acc[ai][bj][m][n], 0, 0, 0); __builtin_amdgcn_s_setprio(0); } while (0)
; #define PG8_WAIT_V(n) asm volatile("s_waitcnt vmcnt(" #n ")" ::: "memory")
; #define PG8_WAIT_L(n) asm volatile("s_waitcnt lgkmcnt(" #n ")" ::: "memory")
; #define PG8_BAR __builtin_amdgcn_s_barrier()
; #define PG8_SCHED __builtin_amdgcn_sched_barrier(0)
; template <class Epi, class Sched, bool ALIGN_EPI = false, bool SP2 = false>
; __device__ __forceinline__ void gemm_phase(PG8_LAS unsigned char* lds, const Gemm g, const Sched S, const Epi E) {
;     ...
;             const bool last = (t == nt - 2);
;             const char* a1 = cA + (size_t)(t + 1) * kstep;
;             const char* a2 = last ? nA : cA + (size_t)(t + 2) * kstep; const char* b2 = last ? nB : cB + (size_t)(t + 2) * kstep;
;             const char* a3 = a2 + kstep; const char* b3 = b2 + kstep;
;             if (last && has_next) S.a_ready(nxt);
;             if constexpr (SP2) {
;             PG8_LDB(B0, 0, 0); PG8_LDB(B1, 0, 1); PG8_SCHED; PG8_LDA(At, 0, 0); PG8_STAGE(PG8_SA(1, 1), a1 + hstep, voffA);
;             PG8_WAIT_V(8); PG8_WAIT_L(0); PG8_BAR; PG8_MMA(0, 0, At, B0); PG8_MMA(0, 1, At, B1); PG8_BAR; PG8_SCHED;
;             PG8_LDA(At, 0, 1); PG8_STAGE(PG8_SB(0, 0), b2, voffB); PG8_STAGE(PG8_SB(0, 1), b2 + hstep, voffB); PG8_STAGE(PG8_SA(0, 0), a2, voffA);
.LBB0_416:
	v_add_u32_e32 v158, 0x10000, v168
	v_add_u32_e32 v171, 0x14000, v168
	ds_read_b128 v[134:137], v158
	ds_read_b128 v[138:141], v158 offset:1024
	ds_read_b128 v[142:145], v158 offset:2048
	ds_read_b128 v[158:161], v158 offset:3072
	ds_read_b128 v[162:165], v171
	ds_read_b128 v[172:175], v171 offset:1024
	ds_read_b128 v[182:185], v171 offset:2048
	ds_read_b128 v[198:201], v171 offset:3072
	s_add_i32 s3, s14, 2
	s_add_u32 s15, s68, s16
	s_addc_u32 s18, s69, s17
	s_add_u32 s20, s66, s16
	s_addc_u32 s21, s67, s17
	s_add_i32 s22, 0, 0x10000
	s_cmp_eq_u32 s89, s14
	s_cselect_b32 s19, s1, s18
	s_cselect_b32 s18, s0, s15
	s_cselect_b32 s15, s71, s21
	s_cselect_b32 s14, s70, s20
	s_add_i32 s20, 0, 0x14000
	v_lshl_add_u64 v[176:177], s[68:69], 0, v[132:133]
	s_add_i32 m0, s80, 0xc000
	ds_read_b128 v[202:205], v170
	ds_read_b128 v[206:209], v170 offset:1024
	ds_read_b128 v[210:213], v170 offset:2048
	ds_read_b128 v[214:217], v170 offset:3072
	ds_read_b128 v[218:221], v170 offset:4096
	ds_read_b128 v[222:225], v170 offset:5120
	ds_read_b128 v[226:229], v170 offset:6144
	ds_read_b128 v[230:233], v170 offset:7168
	global_load_lds_dwordx4 v[176:177], off
	v_lshl_add_u64 v[176:177], s[68:69], 0, v[130:131]
	s_add_i32 m0, s80, 0xe000
	s_nop 0
	global_load_lds_dwordx4 v[176:177], off
	s_waitcnt vmcnt(8)
	s_waitcnt lgkmcnt(0)
	s_barrier
	s_setprio 1
	s_waitcnt lgkmcnt(0)
	v_mfma_f32_16x16x32_bf16 v[58:61], v[134:137], v[202:205], v[58:61]
	v_mfma_f32_16x16x32_bf16 v[50:53], v[142:145], v[202:205], v[50:53]
	v_mfma_f32_16x16x32_bf16 v[14:17], v[134:137], v[210:213], v[14:17]
	v_mfma_f32_16x16x32_bf16 v[10:13], v[142:145], v[210:213], v[10:13]
	v_mfma_f32_16x16x32_bf16 v[30:33], v[134:137], v[218:221], v[30:33]
	v_mfma_f32_16x16x32_bf16 v[26:29], v[142:145], v[218:221], v[26:29]
	v_mfma_f32_16x16x32_bf16 v[46:49], v[134:137], v[226:229], v[46:49]
	v_mfma_f32_16x16x32_bf16 v[42:45], v[142:145], v[226:229], v[42:45]
	v_mfma_f32_16x16x32_bf16 v[58:61], v[138:141], v[206:209], v[58:61]
	v_mfma_f32_16x16x32_bf16 v[50:53], v[158:161], v[206:209], v[50:53]
	v_mfma_f32_16x16x32_bf16 v[14:17], v[138:141], v[214:217], v[14:17]
	v_mfma_f32_16x16x32_bf16 v[10:13], v[158:161], v[214:217], v[10:13]
	v_mfma_f32_16x16x32_bf16 v[30:33], v[138:141], v[222:225], v[30:33]
	v_mfma_f32_16x16x32_bf16 v[26:29], v[158:161], v[222:225], v[26:29]
	v_mfma_f32_16x16x32_bf16 v[46:49], v[138:141], v[230:233], v[46:49]
	v_mfma_f32_16x16x32_bf16 v[42:45], v[158:161], v[230:233], v[42:45]
	s_setprio 0
	s_setprio 1
	v_mfma_f32_16x16x32_bf16 v[6:9], v[162:165], v[202:205], v[6:9]
	v_mfma_f32_16x16x32_bf16 v[2:5], v[182:185], v[202:205], v[2:5]
	v_mfma_f32_16x16x32_bf16 v[22:25], v[162:165], v[210:213], v[22:25]
	v_mfma_f32_16x16x32_bf16 v[18:21], v[182:185], v[210:213], v[18:21]
	v_mfma_f32_16x16x32_bf16 v[38:41], v[162:165], v[218:221], v[38:41]
	v_mfma_f32_16x16x32_bf16 v[34:37], v[182:185], v[218:221], v[34:37]
	v_mfma_f32_16x16x32_bf16 v[62:65], v[162:165], v[226:229], v[62:65]
	v_mfma_f32_16x16x32_bf16 v[54:57], v[182:185], v[226:229], v[54:57]
	v_mfma_f32_16x16x32_bf16 v[6:9], v[172:175], v[206:209], v[6:9]
	v_mfma_f32_16x16x32_bf16 v[2:5], v[198:201], v[206:209], v[2:5]
	v_mfma_f32_16x16x32_bf16 v[22:25], v[172:175], v[214:217], v[22:25]
	v_mfma_f32_16x16x32_bf16 v[18:21], v[198:201], v[214:217], v[18:21]
	v_mfma_f32_16x16x32_bf16 v[38:41], v[172:175], v[222:225], v[38:41]
	v_mfma_f32_16x16x32_bf16 v[34:37], v[198:201], v[222:225], v[34:37]
	v_mfma_f32_16x16x32_bf16 v[62:65], v[172:175], v[230:233], v[62:65]
	v_mfma_f32_16x16x32_bf16 v[54:57], v[198:201], v[230:233], v[54:57]
	s_setprio 0
	s_barrier
	s_add_i32 s21, s22, s79
	v_lshl_add_u64 v[176:177], s[14:15], 0, v[148:149]
	s_mov_b32 m0, s21
	ds_read_b128 v[202:205], v170 offset:16384
	ds_read_b128 v[206:209], v170 offset:17408
	ds_read_b128 v[210:213], v170 offset:18432
	ds_read_b128 v[214:217], v170 offset:19456
	ds_read_b128 v[218:221], v170 offset:20480
	ds_read_b128 v[222:225], v170 offset:21504
	ds_read_b128 v[226:229], v170 offset:22528
	ds_read_b128 v[230:233], v170 offset:23552
	global_load_lds_dwordx4 v[176:177], off
	s_add_i32 m0, s21, 0x2000
	v_lshl_add_u64 v[234:235], s[14:15], 0, v[152:153]
	s_add_u32 s14, s14, s28
	s_addc_u32 s15, s15, 0
	s_add_i32 s20, s20, s79
	global_load_lds_dwordx4 v[234:235], off
	v_lshl_add_u64 v[236:237], s[14:15], 0, v[148:149]
	s_mov_b32 m0, s20
	v_lshl_add_u64 v[238:239], s[14:15], 0, v[152:153]
	global_load_lds_dwordx4 v[236:237], off
	s_add_i32 m0, s20, 0x2000
	v_lshl_add_u64 v[240:241], s[18:19], 0, v[146:147]
	global_load_lds_dwordx4 v[238:239], off
	s_mov_b32 m0, s80
	v_lshl_add_u64 v[242:243], s[18:19], 0, v[150:151]
	global_load_lds_dwordx4 v[240:241], off
	s_mov_b32 m0, s81
	s_nop 0
	global_load_lds_dwordx4 v[242:243], off
	s_waitcnt vmcnt(8)
	s_waitcnt lgkmcnt(0)
	s_barrier
; #define PG8_STAGE(bufoff, gbase, voff) do { _Pragma("unroll") for (int _i = 0; _i < 2; ++_i) \
;         __builtin_amdgcn_global_load_lds((const unsigned*)((const char*)(gbase) + (voff)[_i]), (PG8_LAS unsigned*)(lds + (bufoff) + ldsw + _i * 8192), 16, 0, 0); } while (0)
; #define PG8_LDA(dst, b, h) do { _Pragma("unroll") for (int m = 0; m < 4; ++m) _Pragma("unroll") for (int k = 0; k < 2; ++k) dst[m][k] = *(const PG8_LAS bf16x8*)(lds + PG8_SA(b, h) + aoff + m * 2048 + k * 1024); } while (0)
; #define PG8_LDB(dst, b, h) do { _Pragma("unroll") for (int n = 0; n < 2; ++n) _Pragma("unroll") for (int k = 0; k < 2; ++k) dst[n][k] = *(const PG8_LAS bf16x8*)(lds + PG8_SB(b, h) + boff + n * 2048 + k * 1024); } while (0)
; #define PG8_MMA(ai, bj, At, Bt) do { __builtin_amdgcn_s_setprio(1); _Pragma("unroll") for (int m = 0; m < 4; ++m) _Pragma("unroll") for (int n = 0; n < 2; ++n) _Pragma("unroll") for (int k = 0; k < 2; ++k) \
;         acc[ai][bj][m][n] = __builtin_amdgcn_mfma_f32_16x16x32_bf16(Bt[n][k], At[m][k], acc[ai][bj][m][n], 0, 0, 0); __builtin_amdgcn_s_setprio(0); } while (0)
; #define PG8_WAIT_V(n) asm volatile("s_waitcnt vmcnt(" #n ")" ::: "memory")
; #define PG8_WAIT_L(n) asm volatile("s_waitcnt lgkmcnt(" #n ")" ::: "memory")
; #define PG8_BAR __builtin_amdgcn_s_barrier()
; #define PG8_SCHED __builtin_amdgcn_sched_barrier(0)
; template <class Epi, class Sched, bool ALIGN_EPI = false, bool SP2 = false>
; __device__ __forceinline__ void gemm_phase(PG8_LAS unsigned char* lds, const Gemm g, const Sched S, const Epi E) {
;     ...
;             PG8_WAIT_V(8); PG8_WAIT_L(0); PG8_BAR; PG8_MMA(1, 0, At, B0); PG8_MMA(1, 1, At, B1); PG8_BAR; PG8_SCHED;
;             PG8_LDB(B0, 1, 0); PG8_LDB(B1, 1, 1); PG8_SCHED; PG8_LDA(At, 1, 0); PG8_STAGE(PG8_SA(0, 1), a2 + hstep, voffA);
;             PG8_WAIT_V(8); PG8_WAIT_L(0); PG8_BAR; PG8_MMA(0, 0, At, B0); PG8_MMA(0, 1, At, B1); PG8_BAR; PG8_SCHED;
	s_setprio 1
	s_waitcnt lgkmcnt(0)
	v_mfma_f32_16x16x32_bf16 v[70:73], v[134:137], v[202:205], v[70:73]
	v_mfma_f32_16x16x32_bf16 v[66:69], v[142:145], v[202:205], v[66:69]
	v_mfma_f32_16x16x32_bf16 v[86:89], v[134:137], v[210:213], v[86:89]
	v_mfma_f32_16x16x32_bf16 v[82:85], v[142:145], v[210:213], v[82:85]
	v_mfma_f32_16x16x32_bf16 v[102:105], v[134:137], v[218:221], v[102:105]
	v_mfma_f32_16x16x32_bf16 v[98:101], v[142:145], v[218:221], v[98:101]
	v_mfma_f32_16x16x32_bf16 v[118:121], v[134:137], v[226:229], v[118:121]
	v_mfma_f32_16x16x32_bf16 v[114:117], v[142:145], v[226:229], v[114:117]
	v_mfma_f32_16x16x32_bf16 v[70:73], v[138:141], v[206:209], v[70:73]
	v_mfma_f32_16x16x32_bf16 v[66:69], v[158:161], v[206:209], v[66:69]
	v_mfma_f32_16x16x32_bf16 v[86:89], v[138:141], v[214:217], v[86:89]
	v_mfma_f32_16x16x32_bf16 v[82:85], v[158:161], v[214:217], v[82:85]
	v_mfma_f32_16x16x32_bf16 v[102:105], v[138:141], v[222:225], v[102:105]
	v_mfma_f32_16x16x32_bf16 v[98:101], v[158:161], v[222:225], v[98:101]
	v_mfma_f32_16x16x32_bf16 v[118:121], v[138:141], v[230:233], v[118:121]
	v_mfma_f32_16x16x32_bf16 v[114:117], v[158:161], v[230:233], v[114:117]
	s_setprio 0
	s_setprio 1
	v_mfma_f32_16x16x32_bf16 v[78:81], v[162:165], v[202:205], v[78:81]
	v_mfma_f32_16x16x32_bf16 v[74:77], v[182:185], v[202:205], v[74:77]
	v_mfma_f32_16x16x32_bf16 v[94:97], v[162:165], v[210:213], v[94:97]
	v_mfma_f32_16x16x32_bf16 v[90:93], v[182:185], v[210:213], v[90:93]
	v_mfma_f32_16x16x32_bf16 v[110:113], v[162:165], v[218:221], v[110:113]
	v_mfma_f32_16x16x32_bf16 v[106:109], v[182:185], v[218:221], v[106:109]
	v_mfma_f32_16x16x32_bf16 v[126:129], v[162:165], v[226:229], v[126:129]
	v_mfma_f32_16x16x32_bf16 v[122:125], v[182:185], v[226:229], v[122:125]
	v_mfma_f32_16x16x32_bf16 v[78:81], v[172:175], v[206:209], v[78:81]
	v_mfma_f32_16x16x32_bf16 v[74:77], v[198:201], v[206:209], v[74:77]
	v_mfma_f32_16x16x32_bf16 v[94:97], v[172:175], v[214:217], v[94:97]
	v_mfma_f32_16x16x32_bf16 v[90:93], v[198:201], v[214:217], v[90:93]
	v_mfma_f32_16x16x32_bf16 v[110:113], v[172:175], v[222:225], v[110:113]
	v_mfma_f32_16x16x32_bf16 v[106:109], v[198:201], v[222:225], v[106:109]
	v_mfma_f32_16x16x32_bf16 v[126:129], v[172:175], v[230:233], v[126:129]
	v_mfma_f32_16x16x32_bf16 v[122:125], v[198:201], v[230:233], v[122:125]
	s_setprio 0
	s_barrier
	v_add_u32_e32 v158, 0x18000, v168
	v_add_u32_e32 v171, 0x1c000, v168
	ds_read_b128 v[134:137], v158
	ds_read_b128 v[138:141], v158 offset:1024
	ds_read_b128 v[142:145], v158 offset:2048
	ds_read_b128 v[158:161], v158 offset:3072
	ds_read_b128 v[162:165], v171
	ds_read_b128 v[172:175], v171 offset:1024
	ds_read_b128 v[182:185], v171 offset:2048
	ds_read_b128 v[198:201], v171 offset:3072
	s_add_i32 s20, 0, 0x18000
	s_add_i32 s21, 0, 0x1c000
	s_add_u32 s14, s18, s28
	s_addc_u32 s15, s19, 0
	s_mov_b32 m0, s82
	v_lshl_add_u64 v[244:245], s[14:15], 0, v[146:147]
	ds_read_b128 v[202:205], v170 offset:32768
	ds_read_b128 v[206:209], v170 offset:33792
	ds_read_b128 v[210:213], v170 offset:34816
	ds_read_b128 v[214:217], v170 offset:35840
	ds_read_b128 v[218:221], v170 offset:36864
	ds_read_b128 v[222:225], v170 offset:37888
	ds_read_b128 v[226:229], v170 offset:38912
	ds_read_b128 v[230:233], v170 offset:39936
	global_load_lds_dwordx4 v[244:245], off
	v_lshl_add_u64 v[244:245], s[14:15], 0, v[150:151]
	s_mov_b32 m0, s83
	s_nop 0
	global_load_lds_dwordx4 v[244:245], off
	s_waitcnt vmcnt(8)
	s_waitcnt lgkmcnt(0)
	s_barrier
	s_setprio 1
	s_waitcnt lgkmcnt(0)
	v_mfma_f32_16x16x32_bf16 v[58:61], v[134:137], v[202:205], v[58:61]
	v_mfma_f32_16x16x32_bf16 v[50:53], v[142:145], v[202:205], v[50:53]
	v_mfma_f32_16x16x32_bf16 v[14:17], v[134:137], v[210:213], v[14:17]
	v_mfma_f32_16x16x32_bf16 v[10:13], v[142:145], v[210:213], v[10:13]
	v_mfma_f32_16x16x32_bf16 v[30:33], v[134:137], v[218:221], v[30:33]
	v_mfma_f32_16x16x32_bf16 v[26:29], v[142:145], v[218:221], v[26:29]
	v_mfma_f32_16x16x32_bf16 v[46:49], v[134:137], v[226:229], v[46:49]
	v_mfma_f32_16x16x32_bf16 v[42:45], v[142:145], v[226:229], v[42:45]
	v_mfma_f32_16x16x32_bf16 v[58:61], v[138:141], v[206:209], v[58:61]
	v_mfma_f32_16x16x32_bf16 v[50:53], v[158:161], v[206:209], v[50:53]
	v_mfma_f32_16x16x32_bf16 v[14:17], v[138:141], v[214:217], v[14:17]
	v_mfma_f32_16x16x32_bf16 v[10:13], v[158:161], v[214:217], v[10:13]
	v_mfma_f32_16x16x32_bf16 v[30:33], v[138:141], v[222:225], v[30:33]
	v_mfma_f32_16x16x32_bf16 v[26:29], v[158:161], v[222:225], v[26:29]
	v_mfma_f32_16x16x32_bf16 v[46:49], v[138:141], v[230:233], v[46:49]
	v_mfma_f32_16x16x32_bf16 v[42:45], v[158:161], v[230:233], v[42:45]
	s_setprio 0
	s_setprio 1
	v_mfma_f32_16x16x32_bf16 v[6:9], v[162:165], v[202:205], v[6:9]
	v_mfma_f32_16x16x32_bf16 v[2:5], v[182:185], v[202:205], v[2:5]
	v_mfma_f32_16x16x32_bf16 v[22:25], v[162:165], v[210:213], v[22:25]
	v_mfma_f32_16x16x32_bf16 v[18:21], v[182:185], v[210:213], v[18:21]
	v_mfma_f32_16x16x32_bf16 v[38:41], v[162:165], v[218:221], v[38:41]
	v_mfma_f32_16x16x32_bf16 v[34:37], v[182:185], v[218:221], v[34:37]
	v_mfma_f32_16x16x32_bf16 v[62:65], v[162:165], v[226:229], v[62:65]
	v_mfma_f32_16x16x32_bf16 v[54:57], v[182:185], v[226:229], v[54:57]
	v_mfma_f32_16x16x32_bf16 v[6:9], v[172:175], v[206:209], v[6:9]
	v_mfma_f32_16x16x32_bf16 v[2:5], v[198:201], v[206:209], v[2:5]
	v_mfma_f32_16x16x32_bf16 v[22:25], v[172:175], v[214:217], v[22:25]
	v_mfma_f32_16x16x32_bf16 v[18:21], v[198:201], v[214:217], v[18:21]
	v_mfma_f32_16x16x32_bf16 v[38:41], v[172:175], v[222:225], v[38:41]
	v_mfma_f32_16x16x32_bf16 v[34:37], v[198:201], v[222:225], v[34:37]
	v_mfma_f32_16x16x32_bf16 v[62:65], v[172:175], v[230:233], v[62:65]
	v_mfma_f32_16x16x32_bf16 v[54:57], v[198:201], v[230:233], v[54:57]
	s_setprio 0
	s_barrier
; #define PG8_STAGE(bufoff, gbase, voff) do { _Pragma("unroll") for (int _i = 0; _i < 2; ++_i) \
;         __builtin_amdgcn_global_load_lds((const unsigned*)((const char*)(gbase) + (voff)[_i]), (PG8_LAS unsigned*)(lds + (bufoff) + ldsw + _i * 8192), 16, 0, 0); } while (0)
; #define PG8_LDA(dst, b, h) do { _Pragma("unroll") for (int m = 0; m < 4; ++m) _Pragma("unroll") for (int k = 0; k < 2; ++k) dst[m][k] = *(const PG8_LAS bf16x8*)(lds + PG8_SA(b, h) + aoff + m * 2048 + k * 1024); } while (0)
; #define PG8_MMA(ai, bj, At, Bt) do { __builtin_amdgcn_s_setprio(1); _Pragma("unroll") for (int m = 0; m < 4; ++m) _Pragma("unroll") for (int n = 0; n < 2; ++n) _Pragma("unroll") for (int k = 0; k < 2; ++k) \
;         acc[ai][bj][m][n] = __builtin_amdgcn_mfma_f32_16x16x32_bf16(Bt[n][k], At[m][k], acc[ai][bj][m][n], 0, 0, 0); __builtin_amdgcn_s_setprio(0); } while (0)
; #define PG8_WAIT_V(n) asm volatile("s_waitcnt vmcnt(" #n ")" ::: "memory")
; #define PG8_WAIT_L(n) asm volatile("s_waitcnt lgkmcnt(" #n ")" ::: "memory")
; #define PG8_BAR __builtin_amdgcn_s_barrier()
; #define PG8_SCHED __builtin_amdgcn_sched_barrier(0)
; template <class Epi, class Sched, bool ALIGN_EPI = false, bool SP2 = false>
; __device__ __forceinline__ void gemm_phase(PG8_LAS unsigned char* lds, const Gemm g, const Sched S, const Epi E) {
;     ...
;             PG8_LDA(At, 1, 1); PG8_STAGE(PG8_SB(1, 0), b3, voffB); PG8_STAGE(PG8_SB(1, 1), b3 + hstep, voffB); PG8_STAGE(PG8_SA(1, 0), a3, voffA);
;             PG8_WAIT_V(8); PG8_WAIT_L(0); PG8_BAR; PG8_MMA(1, 0, At, B0); PG8_MMA(1, 1, At, B1); PG8_BAR; PG8_SCHED;
	s_add_i32 s14, s20, s79
	v_lshl_add_u64 v[176:177], v[176:177], 0, s[12:13]
	s_mov_b32 m0, s14
	ds_read_b128 v[202:205], v170 offset:49152
	ds_read_b128 v[206:209], v170 offset:50176
	ds_read_b128 v[210:213], v170 offset:51200
	ds_read_b128 v[214:217], v170 offset:52224
	ds_read_b128 v[218:221], v170 offset:53248
	ds_read_b128 v[222:225], v170 offset:54272
	ds_read_b128 v[226:229], v170 offset:55296
	ds_read_b128 v[230:233], v170 offset:56320
	global_load_lds_dwordx4 v[176:177], off
	v_lshl_add_u64 v[176:177], v[234:235], 0, s[12:13]
	s_add_i32 m0, s14, 0x2000
	s_add_i32 s14, s21, s79
	global_load_lds_dwordx4 v[176:177], off
	v_lshl_add_u64 v[176:177], v[236:237], 0, s[12:13]
	s_mov_b32 m0, s14
	s_nop 0
	global_load_lds_dwordx4 v[176:177], off
	v_lshl_add_u64 v[176:177], v[238:239], 0, s[12:13]
	s_add_i32 m0, s14, 0x2000
	s_nop 0
	global_load_lds_dwordx4 v[176:177], off
	v_lshl_add_u64 v[176:177], v[240:241], 0, s[12:13]
	s_mov_b32 m0, s84
	s_nop 0
	global_load_lds_dwordx4 v[176:177], off
	v_lshl_add_u64 v[176:177], v[242:243], 0, s[12:13]
	s_mov_b32 m0, s85
	s_nop 0
	global_load_lds_dwordx4 v[176:177], off
	s_waitcnt vmcnt(8)
	s_waitcnt lgkmcnt(0)
	s_barrier
	s_setprio 1
	s_waitcnt lgkmcnt(0)
	v_mfma_f32_16x16x32_bf16 v[70:73], v[134:137], v[202:205], v[70:73]
	v_mfma_f32_16x16x32_bf16 v[66:69], v[142:145], v[202:205], v[66:69]
	v_mfma_f32_16x16x32_bf16 v[86:89], v[134:137], v[210:213], v[86:89]
	v_mfma_f32_16x16x32_bf16 v[82:85], v[142:145], v[210:213], v[82:85]
	v_mfma_f32_16x16x32_bf16 v[102:105], v[134:137], v[218:221], v[102:105]
	v_mfma_f32_16x16x32_bf16 v[98:101], v[142:145], v[218:221], v[98:101]
	v_mfma_f32_16x16x32_bf16 v[118:121], v[134:137], v[226:229], v[118:121]
	v_mfma_f32_16x16x32_bf16 v[114:117], v[142:145], v[226:229], v[114:117]
	v_mfma_f32_16x16x32_bf16 v[70:73], v[138:141], v[206:209], v[70:73]
	v_mfma_f32_16x16x32_bf16 v[66:69], v[158:161], v[206:209], v[66:69]
	v_mfma_f32_16x16x32_bf16 v[86:89], v[138:141], v[214:217], v[86:89]
	v_mfma_f32_16x16x32_bf16 v[82:85], v[158:161], v[214:217], v[82:85]
	v_mfma_f32_16x16x32_bf16 v[102:105], v[138:141], v[222:225], v[102:105]
	v_mfma_f32_16x16x32_bf16 v[98:101], v[158:161], v[222:225], v[98:101]
	v_mfma_f32_16x16x32_bf16 v[118:121], v[138:141], v[230:233], v[118:121]
	v_mfma_f32_16x16x32_bf16 v[114:117], v[158:161], v[230:233], v[114:117]
	s_setprio 0
	s_setprio 1
	v_mfma_f32_16x16x32_bf16 v[78:81], v[162:165], v[202:205], v[78:81]
	v_mfma_f32_16x16x32_bf16 v[74:77], v[182:185], v[202:205], v[74:77]
	v_mfma_f32_16x16x32_bf16 v[94:97], v[162:165], v[210:213], v[94:97]
	v_mfma_f32_16x16x32_bf16 v[90:93], v[182:185], v[210:213], v[90:93]
	v_mfma_f32_16x16x32_bf16 v[110:113], v[162:165], v[218:221], v[110:113]
	v_mfma_f32_16x16x32_bf16 v[106:109], v[182:185], v[218:221], v[106:109]
	v_mfma_f32_16x16x32_bf16 v[126:129], v[162:165], v[226:229], v[126:129]
	v_mfma_f32_16x16x32_bf16 v[122:125], v[182:185], v[226:229], v[122:125]
	v_mfma_f32_16x16x32_bf16 v[78:81], v[172:175], v[206:209], v[78:81]
	v_mfma_f32_16x16x32_bf16 v[74:77], v[198:201], v[206:209], v[74:77]
	v_mfma_f32_16x16x32_bf16 v[94:97], v[172:175], v[214:217], v[94:97]
	v_mfma_f32_16x16x32_bf16 v[90:93], v[198:201], v[214:217], v[90:93]
	v_mfma_f32_16x16x32_bf16 v[110:113], v[172:175], v[222:225], v[110:113]
	v_mfma_f32_16x16x32_bf16 v[106:109], v[198:201], v[222:225], v[106:109]
	v_mfma_f32_16x16x32_bf16 v[126:129], v[172:175], v[230:233], v[126:129]
	v_mfma_f32_16x16x32_bf16 v[122:125], v[198:201], v[230:233], v[122:125]
	s_setprio 0
	s_add_u32 s16, s16, 0x100
	s_addc_u32 s17, s17, 0
	v_lshl_add_u64 v[132:133], v[132:133], 0, s[30:31]
	v_lshl_add_u64 v[130:131], v[130:131], 0, s[30:31]
	s_cmp_ge_u32 s3, s88
	s_mov_b32 s14, s3
	s_barrier
	s_cbranch_scc0 .LBB0_416
	s_and_b64 vcc, exec, s[62:63]
	s_cbranch_vccz .LBB0_419
	s_barrier

; #define PG8_STAGE(bufoff, gbase, voff) do { _Pragma("unroll") for (int _i = 0; _i < 2; ++_i) \
;         __builtin_amdgcn_global_load_lds((const unsigned*)((const char*)(gbase) + (voff)[_i]), (PG8_LAS unsigned*)(lds + (bufoff) + ldsw + _i * 8192), 16, 0, 0); } while (0)
; #define PG8_LDA(dst, b, h) do { _Pragma("unroll") for (int m = 0; m < 4; ++m) _Pragma("unroll") for (int k = 0; k < 2; ++k) dst[m][k] = *(const PG8_LAS bf16x8*)(lds + PG8_SA(b, h) + aoff + m * 2048 + k * 1024); } while (0)
; #define PG8_LDB(dst, b, h) do { _Pragma("unroll") for (int n = 0; n < 2; ++n) _Pragma("unroll") for (int k = 0; k < 2; ++k) dst[n][k] = *(const PG8_LAS bf16x8*)(lds + PG8_SB(b, h) + boff + n * 2048 + k * 1024); } while (0)
; #define PG8_MMA(ai, bj, At, Bt) do { __builtin_amdgcn_s_setprio(1); _Pragma("unroll") for (int m = 0; m < 4; ++m) _Pragma("unroll") for (int n = 0; n < 2; ++n) _Pragma("unroll") for (int k = 0; k < 2; ++k) \
;         acc[ai][bj][m][n] = __builtin_amdgcn_mfma_f32_16x16x32_bf16(Bt[n][k], At[m][k], acc[ai][bj][m][n], 0, 0, 0); __builtin_amdgcn_s_setprio(0); } while (0)
; #define PG8_WAIT_V(n) asm volatile("s_waitcnt vmcnt(" #n ")" ::: "memory")
; #define PG8_WAIT_L(n) asm volatile("s_waitcnt lgkmcnt(" #n ")" ::: "memory")
; #define PG8_BAR __builtin_amdgcn_s_barrier()
; #define PG8_SCHED __builtin_amdgcn_sched_barrier(0)
; template <class Epi, class Sched, bool ALIGN_EPI = false, bool SP2 = false>
; __device__ __forceinline__ void gemm_phase(PG8_LAS unsigned char* lds, const Gemm g, const Sched S, const Epi E) {
;     ...
;             const bool last = (t == nt - 2);
;             const char* a1 = cA + (size_t)(t + 1) * kstep;
;             const char* a2 = last ? nA : cA + (size_t)(t + 2) * kstep; const char* b2 = last ? nB : cB + (size_t)(t + 2) * kstep;
;             const char* a3 = a2 + kstep; const char* b3 = b2 + kstep;
;             if (last && has_next) S.a_ready(nxt);
;             if constexpr (SP2) {
;             PG8_LDB(B0, 0, 0); PG8_LDB(B1, 0, 1); PG8_SCHED; PG8_LDA(At, 0, 0); PG8_STAGE(PG8_SA(1, 1), a1 + hstep, voffA);
;             PG8_WAIT_V(8); PG8_WAIT_L(0); PG8_BAR; PG8_MMA(0, 0, At, B0); PG8_MMA(0, 1, At, B1); PG8_BAR; PG8_SCHED;
;             PG8_LDA(At, 0, 1); PG8_STAGE(PG8_SB(0, 0), b2, voffB); PG8_STAGE(PG8_SB(0, 1), b2 + hstep, voffB); PG8_STAGE(PG8_SA(0, 0), a2, voffA);
.LBB0_538:
	v_add_u32_e32 v155, 0x10000, v152
	ds_read_b128 v[146:149], v155
	ds_read_b128 v[156:159], v155 offset:1024
	ds_read_b128 v[160:163], v155 offset:2048
	ds_read_b128 v[164:167], v155 offset:3072
	v_add_u32_e32 v155, 0x14000, v152
	ds_read_b128 v[168:171], v155
	ds_read_b128 v[172:175], v155 offset:1024
	ds_read_b128 v[182:185], v155 offset:2048
	ds_read_b128 v[198:201], v155 offset:3072
	s_add_i32 s3, s14, 2
	s_add_u32 s15, s68, s16
	s_addc_u32 s18, s69, s17
	s_add_u32 s20, s66, s16
	s_addc_u32 s21, s67, s17
	s_add_i32 s22, 0, 0x10000
	s_cmp_eq_u32 s81, s14
	s_cselect_b32 s19, s1, s18
	s_cselect_b32 s18, s0, s15
	s_cselect_b32 s15, s55, s21
	s_cselect_b32 s14, s54, s20
	s_add_i32 s20, 0, 0x14000
	v_lshl_add_u64 v[176:177], s[68:69], 0, v[144:145]
	s_add_i32 m0, s72, 0xc000
	ds_read_b128 v[202:205], v154
	ds_read_b128 v[206:209], v154 offset:1024
	ds_read_b128 v[210:213], v154 offset:2048
	ds_read_b128 v[214:217], v154 offset:3072
	ds_read_b128 v[218:221], v154 offset:4096
	ds_read_b128 v[222:225], v154 offset:5120
	ds_read_b128 v[226:229], v154 offset:6144
	ds_read_b128 v[230:233], v154 offset:7168
	global_load_lds_dwordx4 v[176:177], off
	v_lshl_add_u64 v[176:177], s[68:69], 0, v[142:143]
	s_add_i32 m0, s72, 0xe000
	s_nop 0
	global_load_lds_dwordx4 v[176:177], off
	s_waitcnt vmcnt(8)
	s_waitcnt lgkmcnt(0)
	s_barrier
	s_setprio 1
	s_waitcnt lgkmcnt(0)
	v_mfma_f32_16x16x32_bf16 v[62:65], v[146:149], v[202:205], v[62:65]
	v_mfma_f32_16x16x32_bf16 v[54:57], v[160:163], v[202:205], v[54:57]
	v_mfma_f32_16x16x32_bf16 v[14:17], v[146:149], v[210:213], v[14:17]
	v_mfma_f32_16x16x32_bf16 v[10:13], v[160:163], v[210:213], v[10:13]
	v_mfma_f32_16x16x32_bf16 v[30:33], v[146:149], v[218:221], v[30:33]
	v_mfma_f32_16x16x32_bf16 v[26:29], v[160:163], v[218:221], v[26:29]
	v_mfma_f32_16x16x32_bf16 v[46:49], v[146:149], v[226:229], v[46:49]
	v_mfma_f32_16x16x32_bf16 v[42:45], v[160:163], v[226:229], v[42:45]
	v_mfma_f32_16x16x32_bf16 v[62:65], v[156:159], v[206:209], v[62:65]
	v_mfma_f32_16x16x32_bf16 v[54:57], v[164:167], v[206:209], v[54:57]
	v_mfma_f32_16x16x32_bf16 v[14:17], v[156:159], v[214:217], v[14:17]
	v_mfma_f32_16x16x32_bf16 v[10:13], v[164:167], v[214:217], v[10:13]
	v_mfma_f32_16x16x32_bf16 v[30:33], v[156:159], v[222:225], v[30:33]
	v_mfma_f32_16x16x32_bf16 v[26:29], v[164:167], v[222:225], v[26:29]
	v_mfma_f32_16x16x32_bf16 v[46:49], v[156:159], v[230:233], v[46:49]
	v_mfma_f32_16x16x32_bf16 v[42:45], v[164:167], v[230:233], v[42:45]
	s_setprio 0
	s_setprio 1
	v_mfma_f32_16x16x32_bf16 v[6:9], v[168:171], v[202:205], v[6:9]
	v_mfma_f32_16x16x32_bf16 v[2:5], v[182:185], v[202:205], v[2:5]
	v_mfma_f32_16x16x32_bf16 v[22:25], v[168:171], v[210:213], v[22:25]
	v_mfma_f32_16x16x32_bf16 v[18:21], v[182:185], v[210:213], v[18:21]
	v_mfma_f32_16x16x32_bf16 v[38:41], v[168:171], v[218:221], v[38:41]
	v_mfma_f32_16x16x32_bf16 v[34:37], v[182:185], v[218:221], v[34:37]
	v_mfma_f32_16x16x32_bf16 v[58:61], v[168:171], v[226:229], v[58:61]
	v_mfma_f32_16x16x32_bf16 v[50:53], v[182:185], v[226:229], v[50:53]
	v_mfma_f32_16x16x32_bf16 v[6:9], v[172:175], v[206:209], v[6:9]
	v_mfma_f32_16x16x32_bf16 v[2:5], v[198:201], v[206:209], v[2:5]
	v_mfma_f32_16x16x32_bf16 v[22:25], v[172:175], v[214:217], v[22:25]
	v_mfma_f32_16x16x32_bf16 v[18:21], v[198:201], v[214:217], v[18:21]
	v_mfma_f32_16x16x32_bf16 v[38:41], v[172:175], v[222:225], v[38:41]
	v_mfma_f32_16x16x32_bf16 v[34:37], v[198:201], v[222:225], v[34:37]
	v_mfma_f32_16x16x32_bf16 v[58:61], v[172:175], v[230:233], v[58:61]
	v_mfma_f32_16x16x32_bf16 v[50:53], v[198:201], v[230:233], v[50:53]
	s_setprio 0
	s_barrier
	s_add_i32 s21, s22, s71
	v_lshl_add_u64 v[176:177], s[14:15], 0, v[0:1]
	s_mov_b32 m0, s21
	ds_read_b128 v[202:205], v154 offset:16384
	ds_read_b128 v[206:209], v154 offset:17408
	ds_read_b128 v[210:213], v154 offset:18432
	ds_read_b128 v[214:217], v154 offset:19456
	ds_read_b128 v[218:221], v154 offset:20480
	ds_read_b128 v[222:225], v154 offset:21504
	ds_read_b128 v[226:229], v154 offset:22528
	ds_read_b128 v[230:233], v154 offset:23552
	global_load_lds_dwordx4 v[176:177], off
	s_add_i32 m0, s21, 0x2000
	v_lshl_add_u64 v[234:235], s[14:15], 0, v[134:135]
	s_add_u32 s14, s14, s28
	s_addc_u32 s15, s15, 0
	s_add_i32 s20, s20, s71
	global_load_lds_dwordx4 v[234:235], off
	v_lshl_add_u64 v[236:237], s[14:15], 0, v[0:1]
	s_mov_b32 m0, s20
	v_lshl_add_u64 v[238:239], s[14:15], 0, v[134:135]
	global_load_lds_dwordx4 v[236:237], off
	s_add_i32 m0, s20, 0x2000
	v_lshl_add_u64 v[240:241], s[18:19], 0, v[130:131]
	global_load_lds_dwordx4 v[238:239], off
	s_mov_b32 m0, s72
	v_lshl_add_u64 v[242:243], s[18:19], 0, v[132:133]
	global_load_lds_dwordx4 v[240:241], off
	s_mov_b32 m0, s73
	s_nop 0
	global_load_lds_dwordx4 v[242:243], off
	s_waitcnt vmcnt(8)
	s_waitcnt lgkmcnt(0)
	s_barrier
; #define PG8_STAGE(bufoff, gbase, voff) do { _Pragma("unroll") for (int _i = 0; _i < 2; ++_i) \
;         __builtin_amdgcn_global_load_lds((const unsigned*)((const char*)(gbase) + (voff)[_i]), (PG8_LAS unsigned*)(lds + (bufoff) + ldsw + _i * 8192), 16, 0, 0); } while (0)
; #define PG8_LDA(dst, b, h) do { _Pragma("unroll") for (int m = 0; m < 4; ++m) _Pragma("unroll") for (int k = 0; k < 2; ++k) dst[m][k] = *(const PG8_LAS bf16x8*)(lds + PG8_SA(b, h) + aoff + m * 2048 + k * 1024); } while (0)
; #define PG8_LDB(dst, b, h) do { _Pragma("unroll") for (int n = 0; n < 2; ++n) _Pragma("unroll") for (int k = 0; k < 2; ++k) dst[n][k] = *(const PG8_LAS bf16x8*)(lds + PG8_SB(b, h) + boff + n * 2048 + k * 1024); } while (0)
; #define PG8_MMA(ai, bj, At, Bt) do { __builtin_amdgcn_s_setprio(1); _Pragma("unroll") for (int m = 0; m < 4; ++m) _Pragma("unroll") for (int n = 0; n < 2; ++n) _Pragma("unroll") for (int k = 0; k < 2; ++k) \
;         acc[ai][bj][m][n] = __builtin_amdgcn_mfma_f32_16x16x32_bf16(Bt[n][k], At[m][k], acc[ai][bj][m][n], 0, 0, 0); __builtin_amdgcn_s_setprio(0); } while (0)
; #define PG8_WAIT_V(n) asm volatile("s_waitcnt vmcnt(" #n ")" ::: "memory")
; #define PG8_WAIT_L(n) asm volatile("s_waitcnt lgkmcnt(" #n ")" ::: "memory")
; #define PG8_BAR __builtin_amdgcn_s_barrier()
; #define PG8_SCHED __builtin_amdgcn_sched_barrier(0)
; template <class Epi, class Sched, bool ALIGN_EPI = false, bool SP2 = false>
; __device__ __forceinline__ void gemm_phase(PG8_LAS unsigned char* lds, const Gemm g, const Sched S, const Epi E) {
;     ...
;             PG8_WAIT_V(8); PG8_WAIT_L(0); PG8_BAR; PG8_MMA(1, 0, At, B0); PG8_MMA(1, 1, At, B1); PG8_BAR; PG8_SCHED;
;             PG8_LDB(B0, 1, 0); PG8_LDB(B1, 1, 1); PG8_SCHED; PG8_LDA(At, 1, 0); PG8_STAGE(PG8_SA(0, 1), a2 + hstep, voffA);
;             PG8_WAIT_V(8); PG8_WAIT_L(0); PG8_BAR; PG8_MMA(0, 0, At, B0); PG8_MMA(0, 1, At, B1); PG8_BAR; PG8_SCHED;
	s_setprio 1
	s_waitcnt lgkmcnt(0)
	v_mfma_f32_16x16x32_bf16 v[70:73], v[146:149], v[202:205], v[70:73]
	v_mfma_f32_16x16x32_bf16 v[66:69], v[160:163], v[202:205], v[66:69]
	v_mfma_f32_16x16x32_bf16 v[86:89], v[146:149], v[210:213], v[86:89]
	v_mfma_f32_16x16x32_bf16 v[82:85], v[160:163], v[210:213], v[82:85]
	v_mfma_f32_16x16x32_bf16 v[102:105], v[146:149], v[218:221], v[102:105]
	v_mfma_f32_16x16x32_bf16 v[98:101], v[160:163], v[218:221], v[98:101]
	v_mfma_f32_16x16x32_bf16 v[118:121], v[146:149], v[226:229], v[118:121]
	v_mfma_f32_16x16x32_bf16 v[114:117], v[160:163], v[226:229], v[114:117]
	v_mfma_f32_16x16x32_bf16 v[70:73], v[156:159], v[206:209], v[70:73]
	v_mfma_f32_16x16x32_bf16 v[66:69], v[164:167], v[206:209], v[66:69]
	v_mfma_f32_16x16x32_bf16 v[86:89], v[156:159], v[214:217], v[86:89]
	v_mfma_f32_16x16x32_bf16 v[82:85], v[164:167], v[214:217], v[82:85]
	v_mfma_f32_16x16x32_bf16 v[102:105], v[156:159], v[222:225], v[102:105]
	v_mfma_f32_16x16x32_bf16 v[98:101], v[164:167], v[222:225], v[98:101]
	v_mfma_f32_16x16x32_bf16 v[118:121], v[156:159], v[230:233], v[118:121]
	v_mfma_f32_16x16x32_bf16 v[114:117], v[164:167], v[230:233], v[114:117]
	s_setprio 0
	s_setprio 1
	v_mfma_f32_16x16x32_bf16 v[78:81], v[168:171], v[202:205], v[78:81]
	v_mfma_f32_16x16x32_bf16 v[74:77], v[182:185], v[202:205], v[74:77]
	v_mfma_f32_16x16x32_bf16 v[94:97], v[168:171], v[210:213], v[94:97]
	v_mfma_f32_16x16x32_bf16 v[90:93], v[182:185], v[210:213], v[90:93]
	v_mfma_f32_16x16x32_bf16 v[110:113], v[168:171], v[218:221], v[110:113]
	v_mfma_f32_16x16x32_bf16 v[106:109], v[182:185], v[218:221], v[106:109]
	v_mfma_f32_16x16x32_bf16 v[126:129], v[168:171], v[226:229], v[126:129]
	v_mfma_f32_16x16x32_bf16 v[122:125], v[182:185], v[226:229], v[122:125]
	v_mfma_f32_16x16x32_bf16 v[78:81], v[172:175], v[206:209], v[78:81]
	v_mfma_f32_16x16x32_bf16 v[74:77], v[198:201], v[206:209], v[74:77]
	v_mfma_f32_16x16x32_bf16 v[94:97], v[172:175], v[214:217], v[94:97]
	v_mfma_f32_16x16x32_bf16 v[90:93], v[198:201], v[214:217], v[90:93]
	v_mfma_f32_16x16x32_bf16 v[110:113], v[172:175], v[222:225], v[110:113]
	v_mfma_f32_16x16x32_bf16 v[106:109], v[198:201], v[222:225], v[106:109]
	v_mfma_f32_16x16x32_bf16 v[126:129], v[172:175], v[230:233], v[126:129]
	v_mfma_f32_16x16x32_bf16 v[122:125], v[198:201], v[230:233], v[122:125]
	s_setprio 0
	s_barrier
	v_add_u32_e32 v155, 0x18000, v152
	ds_read_b128 v[146:149], v155
	ds_read_b128 v[156:159], v155 offset:1024
	ds_read_b128 v[160:163], v155 offset:2048
	ds_read_b128 v[164:167], v155 offset:3072
	v_add_u32_e32 v155, 0x1c000, v152
	ds_read_b128 v[168:171], v155
	ds_read_b128 v[172:175], v155 offset:1024
	ds_read_b128 v[182:185], v155 offset:2048
	ds_read_b128 v[198:201], v155 offset:3072
	s_add_i32 s20, 0, 0x18000
	s_add_i32 s21, 0, 0x1c000
	s_add_u32 s14, s18, s28
	s_addc_u32 s15, s19, 0
	s_mov_b32 m0, s74
	v_lshl_add_u64 v[244:245], s[14:15], 0, v[130:131]
	ds_read_b128 v[202:205], v154 offset:32768
	ds_read_b128 v[206:209], v154 offset:33792
	ds_read_b128 v[210:213], v154 offset:34816
	ds_read_b128 v[214:217], v154 offset:35840
	ds_read_b128 v[218:221], v154 offset:36864
	ds_read_b128 v[222:225], v154 offset:37888
	ds_read_b128 v[226:229], v154 offset:38912
	ds_read_b128 v[230:233], v154 offset:39936
	global_load_lds_dwordx4 v[244:245], off
	v_lshl_add_u64 v[244:245], s[14:15], 0, v[132:133]
	s_mov_b32 m0, s75
	s_nop 0
	global_load_lds_dwordx4 v[244:245], off
	s_waitcnt vmcnt(8)
	s_waitcnt lgkmcnt(0)
	s_barrier
	s_setprio 1
	s_waitcnt lgkmcnt(0)
	v_mfma_f32_16x16x32_bf16 v[62:65], v[146:149], v[202:205], v[62:65]
	v_mfma_f32_16x16x32_bf16 v[54:57], v[160:163], v[202:205], v[54:57]
	v_mfma_f32_16x16x32_bf16 v[14:17], v[146:149], v[210:213], v[14:17]
	v_mfma_f32_16x16x32_bf16 v[10:13], v[160:163], v[210:213], v[10:13]
	v_mfma_f32_16x16x32_bf16 v[30:33], v[146:149], v[218:221], v[30:33]
	v_mfma_f32_16x16x32_bf16 v[26:29], v[160:163], v[218:221], v[26:29]
	v_mfma_f32_16x16x32_bf16 v[46:49], v[146:149], v[226:229], v[46:49]
	v_mfma_f32_16x16x32_bf16 v[42:45], v[160:163], v[226:229], v[42:45]
	v_mfma_f32_16x16x32_bf16 v[62:65], v[156:159], v[206:209], v[62:65]
	v_mfma_f32_16x16x32_bf16 v[54:57], v[164:167], v[206:209], v[54:57]
	v_mfma_f32_16x16x32_bf16 v[14:17], v[156:159], v[214:217], v[14:17]
	v_mfma_f32_16x16x32_bf16 v[10:13], v[164:167], v[214:217], v[10:13]
	v_mfma_f32_16x16x32_bf16 v[30:33], v[156:159], v[222:225], v[30:33]
	v_mfma_f32_16x16x32_bf16 v[26:29], v[164:167], v[222:225], v[26:29]
	v_mfma_f32_16x16x32_bf16 v[46:49], v[156:159], v[230:233], v[46:49]
	v_mfma_f32_16x16x32_bf16 v[42:45], v[164:167], v[230:233], v[42:45]
	s_setprio 0
	s_setprio 1
	v_mfma_f32_16x16x32_bf16 v[6:9], v[168:171], v[202:205], v[6:9]
	v_mfma_f32_16x16x32_bf16 v[2:5], v[182:185], v[202:205], v[2:5]
	v_mfma_f32_16x16x32_bf16 v[22:25], v[168:171], v[210:213], v[22:25]
	v_mfma_f32_16x16x32_bf16 v[18:21], v[182:185], v[210:213], v[18:21]
	v_mfma_f32_16x16x32_bf16 v[38:41], v[168:171], v[218:221], v[38:41]
	v_mfma_f32_16x16x32_bf16 v[34:37], v[182:185], v[218:221], v[34:37]
	v_mfma_f32_16x16x32_bf16 v[58:61], v[168:171], v[226:229], v[58:61]
	v_mfma_f32_16x16x32_bf16 v[50:53], v[182:185], v[226:229], v[50:53]
	v_mfma_f32_16x16x32_bf16 v[6:9], v[172:175], v[206:209], v[6:9]
	v_mfma_f32_16x16x32_bf16 v[2:5], v[198:201], v[206:209], v[2:5]
	v_mfma_f32_16x16x32_bf16 v[22:25], v[172:175], v[214:217], v[22:25]
	v_mfma_f32_16x16x32_bf16 v[18:21], v[198:201], v[214:217], v[18:21]
	v_mfma_f32_16x16x32_bf16 v[38:41], v[172:175], v[222:225], v[38:41]
	v_mfma_f32_16x16x32_bf16 v[34:37], v[198:201], v[222:225], v[34:37]
	v_mfma_f32_16x16x32_bf16 v[58:61], v[172:175], v[230:233], v[58:61]
	v_mfma_f32_16x16x32_bf16 v[50:53], v[198:201], v[230:233], v[50:53]
	s_setprio 0
	s_barrier
; #define PG8_STAGE(bufoff, gbase, voff) do { _Pragma("unroll") for (int _i = 0; _i < 2; ++_i) \
;         __builtin_amdgcn_global_load_lds((const unsigned*)((const char*)(gbase) + (voff)[_i]), (PG8_LAS unsigned*)(lds + (bufoff) + ldsw + _i * 8192), 16, 0, 0); } while (0)
; #define PG8_LDA(dst, b, h) do { _Pragma("unroll") for (int m = 0; m < 4; ++m) _Pragma("unroll") for (int k = 0; k < 2; ++k) dst[m][k] = *(const PG8_LAS bf16x8*)(lds + PG8_SA(b, h) + aoff + m * 2048 + k * 1024); } while (0)
; #define PG8_MMA(ai, bj, At, Bt) do { __builtin_amdgcn_s_setprio(1); _Pragma("unroll") for (int m = 0; m < 4; ++m) _Pragma("unroll") for (int n = 0; n < 2; ++n) _Pragma("unroll") for (int k = 0; k < 2; ++k) \
;         acc[ai][bj][m][n] = __builtin_amdgcn_mfma_f32_16x16x32_bf16(Bt[n][k], At[m][k], acc[ai][bj][m][n], 0, 0, 0); __builtin_amdgcn_s_setprio(0); } while (0)
; #define PG8_WAIT_V(n) asm volatile("s_waitcnt vmcnt(" #n ")" ::: "memory")
; #define PG8_WAIT_L(n) asm volatile("s_waitcnt lgkmcnt(" #n ")" ::: "memory")
; #define PG8_BAR __builtin_amdgcn_s_barrier()
; #define PG8_SCHED __builtin_amdgcn_sched_barrier(0)
; template <class Epi, class Sched, bool ALIGN_EPI = false, bool SP2 = false>
; __device__ __forceinline__ void gemm_phase(PG8_LAS unsigned char* lds, const Gemm g, const Sched S, const Epi E) {
;     ...
;             PG8_LDA(At, 1, 1); PG8_STAGE(PG8_SB(1, 0), b3, voffB); PG8_STAGE(PG8_SB(1, 1), b3 + hstep, voffB); PG8_STAGE(PG8_SA(1, 0), a3, voffA);
;             PG8_WAIT_V(8); PG8_WAIT_L(0); PG8_BAR; PG8_MMA(1, 0, At, B0); PG8_MMA(1, 1, At, B1); PG8_BAR; PG8_SCHED;
	s_add_i32 s14, s20, s71
	v_lshl_add_u64 v[176:177], v[176:177], 0, s[12:13]
	s_mov_b32 m0, s14
	ds_read_b128 v[202:205], v154 offset:49152
	ds_read_b128 v[206:209], v154 offset:50176
	ds_read_b128 v[210:213], v154 offset:51200
	ds_read_b128 v[214:217], v154 offset:52224
	ds_read_b128 v[218:221], v154 offset:53248
	ds_read_b128 v[222:225], v154 offset:54272
	ds_read_b128 v[226:229], v154 offset:55296
	ds_read_b128 v[230:233], v154 offset:56320
	global_load_lds_dwordx4 v[176:177], off
	v_lshl_add_u64 v[176:177], v[234:235], 0, s[12:13]
	s_add_i32 m0, s14, 0x2000
	s_add_i32 s14, s21, s71
	global_load_lds_dwordx4 v[176:177], off
	v_lshl_add_u64 v[176:177], v[236:237], 0, s[12:13]
	s_mov_b32 m0, s14
	s_nop 0
	global_load_lds_dwordx4 v[176:177], off
	v_lshl_add_u64 v[176:177], v[238:239], 0, s[12:13]
	s_add_i32 m0, s14, 0x2000
	s_nop 0
	global_load_lds_dwordx4 v[176:177], off
	v_lshl_add_u64 v[176:177], v[240:241], 0, s[12:13]
	s_mov_b32 m0, s77
	s_nop 0
	global_load_lds_dwordx4 v[176:177], off
	v_lshl_add_u64 v[176:177], v[242:243], 0, s[12:13]
	s_mov_b32 m0, s78
	s_nop 0
	global_load_lds_dwordx4 v[176:177], off
	s_waitcnt vmcnt(8)
	s_waitcnt lgkmcnt(0)
	s_barrier
	s_setprio 1
	s_waitcnt lgkmcnt(0)
	v_mfma_f32_16x16x32_bf16 v[70:73], v[146:149], v[202:205], v[70:73]
	v_mfma_f32_16x16x32_bf16 v[66:69], v[160:163], v[202:205], v[66:69]
	v_mfma_f32_16x16x32_bf16 v[86:89], v[146:149], v[210:213], v[86:89]
	v_mfma_f32_16x16x32_bf16 v[82:85], v[160:163], v[210:213], v[82:85]
	v_mfma_f32_16x16x32_bf16 v[102:105], v[146:149], v[218:221], v[102:105]
	v_mfma_f32_16x16x32_bf16 v[98:101], v[160:163], v[218:221], v[98:101]
	v_mfma_f32_16x16x32_bf16 v[118:121], v[146:149], v[226:229], v[118:121]
	v_mfma_f32_16x16x32_bf16 v[114:117], v[160:163], v[226:229], v[114:117]
	v_mfma_f32_16x16x32_bf16 v[70:73], v[156:159], v[206:209], v[70:73]
	v_mfma_f32_16x16x32_bf16 v[66:69], v[164:167], v[206:209], v[66:69]
	v_mfma_f32_16x16x32_bf16 v[86:89], v[156:159], v[214:217], v[86:89]
	v_mfma_f32_16x16x32_bf16 v[82:85], v[164:167], v[214:217], v[82:85]
	v_mfma_f32_16x16x32_bf16 v[102:105], v[156:159], v[222:225], v[102:105]
	v_mfma_f32_16x16x32_bf16 v[98:101], v[164:167], v[222:225], v[98:101]
	v_mfma_f32_16x16x32_bf16 v[118:121], v[156:159], v[230:233], v[118:121]
	v_mfma_f32_16x16x32_bf16 v[114:117], v[164:167], v[230:233], v[114:117]
	s_setprio 0
	s_setprio 1
	v_mfma_f32_16x16x32_bf16 v[78:81], v[168:171], v[202:205], v[78:81]
	v_mfma_f32_16x16x32_bf16 v[74:77], v[182:185], v[202:205], v[74:77]
	v_mfma_f32_16x16x32_bf16 v[94:97], v[168:171], v[210:213], v[94:97]
	v_mfma_f32_16x16x32_bf16 v[90:93], v[182:185], v[210:213], v[90:93]
	v_mfma_f32_16x16x32_bf16 v[110:113], v[168:171], v[218:221], v[110:113]
	v_mfma_f32_16x16x32_bf16 v[106:109], v[182:185], v[218:221], v[106:109]
	v_mfma_f32_16x16x32_bf16 v[126:129], v[168:171], v[226:229], v[126:129]
	v_mfma_f32_16x16x32_bf16 v[122:125], v[182:185], v[226:229], v[122:125]
	v_mfma_f32_16x16x32_bf16 v[78:81], v[172:175], v[206:209], v[78:81]
	v_mfma_f32_16x16x32_bf16 v[74:77], v[198:201], v[206:209], v[74:77]
	v_mfma_f32_16x16x32_bf16 v[94:97], v[172:175], v[214:217], v[94:97]
	v_mfma_f32_16x16x32_bf16 v[90:93], v[198:201], v[214:217], v[90:93]
	v_mfma_f32_16x16x32_bf16 v[110:113], v[172:175], v[222:225], v[110:113]
	v_mfma_f32_16x16x32_bf16 v[106:109], v[198:201], v[222:225], v[106:109]
	v_mfma_f32_16x16x32_bf16 v[126:129], v[172:175], v[230:233], v[126:129]
	v_mfma_f32_16x16x32_bf16 v[122:125], v[198:201], v[230:233], v[122:125]
	s_setprio 0
	s_add_u32 s16, s16, 0x100
	s_addc_u32 s17, s17, 0
	v_lshl_add_u64 v[144:145], v[144:145], 0, s[88:89]
	v_lshl_add_u64 v[142:143], v[142:143], 0, s[88:89]
	s_cmp_ge_u32 s3, s76
	s_mov_b32 s14, s3
	s_barrier
	s_cbranch_scc0 .LBB0_538
	s_and_b64 vcc, exec, s[62:63]
	s_cbranch_vccz .LBB0_541
	s_barrier
